# sc0 cache policy on the 128 GEMM LDS-DMA loads (streaming tiles have no per-CU L1 reuse)
# speedup vs baseline: 1.0024x; 1.0024x over previous
.LBB0_200:
	ds_read_b128 v[148:151], v169
	ds_read_b128 v[152:155], v169 offset:1024
	ds_read_b128 v[156:159], v169 offset:2048
	ds_read_b128 v[160:163], v169 offset:3072
	ds_read_b128 v[174:177], v170
	ds_read_b128 v[178:181], v170 offset:1024
	ds_read_b128 v[182:185], v170 offset:2048
	ds_read_b128 v[186:189], v170 offset:3072
	s_add_u32 s26, s6, 0xfff00800
	s_addc_u32 s27, s7, -1
	s_cmp_eq_u32 s34, 60
	s_cselect_b32 s29, s17, s27
	s_cselect_b32 s28, s23, s26
	s_cselect_b32 s27, s15, s31
	s_cselect_b32 s26, s25, s30
	v_lshl_add_u64 v[190:191], s[6:7], 0, v[138:139]
	s_add_i32 m0, s41, 0xc000
	s_nop 0
	global_load_lds_dwordx4 v[190:191], off sc0
	v_lshl_add_u64 v[190:191], s[6:7], 0, v[140:141]
	s_add_i32 m0, s41, 0xe000
	s_nop 0
	global_load_lds_dwordx4 v[190:191], off sc0
	ds_read_b128 v[190:193], v171
	ds_read_b128 v[194:197], v171 offset:1024
	ds_read_b128 v[198:201], v171 offset:2048
	ds_read_b128 v[202:205], v171 offset:3072
	ds_read_b128 v[206:209], v171 offset:4096
	ds_read_b128 v[210:213], v171 offset:5120
	ds_read_b128 v[214:217], v171 offset:6144
	ds_read_b128 v[218:221], v171 offset:7168
	s_waitcnt vmcnt(8)
	s_waitcnt lgkmcnt(0)
	s_barrier
	v_mfma_f32_16x16x32_bf16 v[124:127], v[148:151], v[190:193], v[124:127]
	v_mfma_f32_16x16x32_bf16 v[124:127], v[152:155], v[194:197], v[124:127]
	v_mfma_f32_16x16x32_bf16 v[120:123], v[160:163], v[194:197], v[120:123]
	v_mfma_f32_16x16x32_bf16 v[120:123], v[156:159], v[190:193], v[120:123]
	v_mfma_f32_16x16x32_bf16 v[60:63], v[174:177], v[190:193], v[60:63]
	v_mfma_f32_16x16x32_bf16 v[60:63], v[178:181], v[194:197], v[60:63]
	v_mfma_f32_16x16x32_bf16 v[56:59], v[186:189], v[194:197], v[56:59]
	v_mfma_f32_16x16x32_bf16 v[56:59], v[182:185], v[190:193], v[56:59]
	v_mfma_f32_16x16x32_bf16 v[48:51], v[182:185], v[198:201], v[48:51]
	v_mfma_f32_16x16x32_bf16 v[48:51], v[186:189], v[202:205], v[48:51]
	v_mfma_f32_16x16x32_bf16 v[52:55], v[178:181], v[202:205], v[52:55]
	v_mfma_f32_16x16x32_bf16 v[52:55], v[174:177], v[198:201], v[52:55]
	v_mfma_f32_16x16x32_bf16 v[112:115], v[156:159], v[198:201], v[112:115]
	v_mfma_f32_16x16x32_bf16 v[112:115], v[160:163], v[202:205], v[112:115]
	v_mfma_f32_16x16x32_bf16 v[116:119], v[152:155], v[202:205], v[116:119]
	v_mfma_f32_16x16x32_bf16 v[116:119], v[148:151], v[198:201], v[116:119]
	v_mfma_f32_16x16x32_bf16 v[108:111], v[148:151], v[206:209], v[108:111]
	v_mfma_f32_16x16x32_bf16 v[108:111], v[152:155], v[210:213], v[108:111]
	v_mfma_f32_16x16x32_bf16 v[104:107], v[160:163], v[210:213], v[104:107]
	v_mfma_f32_16x16x32_bf16 v[104:107], v[156:159], v[206:209], v[104:107]
	v_mfma_f32_16x16x32_bf16 v[44:47], v[174:177], v[206:209], v[44:47]
	v_mfma_f32_16x16x32_bf16 v[44:47], v[178:181], v[210:213], v[44:47]
	v_mfma_f32_16x16x32_bf16 v[40:43], v[186:189], v[210:213], v[40:43]
	v_mfma_f32_16x16x32_bf16 v[40:43], v[182:185], v[206:209], v[40:43]
	v_mfma_f32_16x16x32_bf16 v[32:35], v[182:185], v[214:217], v[32:35]
	v_mfma_f32_16x16x32_bf16 v[32:35], v[186:189], v[218:221], v[32:35]
	v_mfma_f32_16x16x32_bf16 v[36:39], v[178:181], v[218:221], v[36:39]
	v_mfma_f32_16x16x32_bf16 v[36:39], v[174:177], v[214:217], v[36:39]
	v_mfma_f32_16x16x32_bf16 v[96:99], v[156:159], v[214:217], v[96:99]
	v_mfma_f32_16x16x32_bf16 v[96:99], v[160:163], v[218:221], v[96:99]
	v_mfma_f32_16x16x32_bf16 v[100:103], v[152:155], v[218:221], v[100:103]
	v_mfma_f32_16x16x32_bf16 v[100:103], v[148:151], v[214:217], v[100:103]
	s_barrier
	s_add_i32 s35, s55, s36
	v_lshl_add_u64 v[222:223], s[26:27], 0, v[130:131]
	s_mov_b32 m0, s35
	v_lshl_add_u64 v[224:225], s[26:27], 0, v[134:135]
	global_load_lds_dwordx4 v[222:223], off sc0
	s_add_i32 m0, s35, 0x2000
	s_add_u32 s58, s26, 0x100000
	s_addc_u32 s59, s27, 0
	s_add_i32 s35, s56, s36
	global_load_lds_dwordx4 v[224:225], off sc0
	v_lshl_add_u64 v[190:191], s[58:59], 0, v[130:131]
	s_mov_b32 m0, s35
	v_lshl_add_u64 v[226:227], s[28:29], 0, v[128:129]
	global_load_lds_dwordx4 v[190:191], off sc0
	v_lshl_add_u64 v[190:191], s[58:59], 0, v[134:135]
	s_add_i32 m0, s35, 0x2000
	v_lshl_add_u64 v[228:229], s[28:29], 0, v[132:133]
	global_load_lds_dwordx4 v[190:191], off sc0
	s_mov_b32 m0, s41
	s_nop 0
	global_load_lds_dwordx4 v[226:227], off sc0
	s_mov_b32 m0, s42
	s_nop 0
	global_load_lds_dwordx4 v[228:229], off sc0
	ds_read_b128 v[190:193], v171 offset:16384
	ds_read_b128 v[194:197], v171 offset:17408
	ds_read_b128 v[198:201], v171 offset:18432
	ds_read_b128 v[202:205], v171 offset:19456
	ds_read_b128 v[206:209], v171 offset:20480
	ds_read_b128 v[210:213], v171 offset:21504
	ds_read_b128 v[214:217], v171 offset:22528
	ds_read_b128 v[218:221], v171 offset:23552
	s_waitcnt vmcnt(8)
	s_waitcnt lgkmcnt(0)
	s_barrier
	v_mfma_f32_16x16x32_bf16 v[92:95], v[148:151], v[190:193], v[92:95]
	v_mfma_f32_16x16x32_bf16 v[92:95], v[152:155], v[194:197], v[92:95]
	v_mfma_f32_16x16x32_bf16 v[88:91], v[160:163], v[194:197], v[88:91]
	v_mfma_f32_16x16x32_bf16 v[88:91], v[156:159], v[190:193], v[88:91]
	v_mfma_f32_16x16x32_bf16 v[28:31], v[174:177], v[190:193], v[28:31]
	v_mfma_f32_16x16x32_bf16 v[28:31], v[178:181], v[194:197], v[28:31]
	v_mfma_f32_16x16x32_bf16 v[24:27], v[186:189], v[194:197], v[24:27]
	v_mfma_f32_16x16x32_bf16 v[24:27], v[182:185], v[190:193], v[24:27]
	v_mfma_f32_16x16x32_bf16 v[16:19], v[182:185], v[198:201], v[16:19]
	v_mfma_f32_16x16x32_bf16 v[16:19], v[186:189], v[202:205], v[16:19]
	v_mfma_f32_16x16x32_bf16 v[20:23], v[178:181], v[202:205], v[20:23]
	v_mfma_f32_16x16x32_bf16 v[20:23], v[174:177], v[198:201], v[20:23]
	v_mfma_f32_16x16x32_bf16 v[80:83], v[156:159], v[198:201], v[80:83]
	v_mfma_f32_16x16x32_bf16 v[80:83], v[160:163], v[202:205], v[80:83]
	v_mfma_f32_16x16x32_bf16 v[84:87], v[152:155], v[202:205], v[84:87]
	v_mfma_f32_16x16x32_bf16 v[84:87], v[148:151], v[198:201], v[84:87]
	v_mfma_f32_16x16x32_bf16 v[76:79], v[148:151], v[206:209], v[76:79]
	v_mfma_f32_16x16x32_bf16 v[76:79], v[152:155], v[210:213], v[76:79]
	v_mfma_f32_16x16x32_bf16 v[72:75], v[160:163], v[210:213], v[72:75]
	v_mfma_f32_16x16x32_bf16 v[72:75], v[156:159], v[206:209], v[72:75]
	v_mfma_f32_16x16x32_bf16 v[12:15], v[174:177], v[206:209], v[12:15]
	v_mfma_f32_16x16x32_bf16 v[12:15], v[178:181], v[210:213], v[12:15]
	v_mfma_f32_16x16x32_bf16 v[8:11], v[186:189], v[210:213], v[8:11]
	v_mfma_f32_16x16x32_bf16 v[8:11], v[182:185], v[206:209], v[8:11]
	v_mfma_f32_16x16x32_bf16 v[0:3], v[182:185], v[214:217], v[0:3]
	v_mfma_f32_16x16x32_bf16 v[0:3], v[186:189], v[218:221], v[0:3]
	v_mfma_f32_16x16x32_bf16 v[4:7], v[178:181], v[218:221], v[4:7]
	v_mfma_f32_16x16x32_bf16 v[4:7], v[174:177], v[214:217], v[4:7]
	v_mfma_f32_16x16x32_bf16 v[64:67], v[156:159], v[214:217], v[64:67]
	v_mfma_f32_16x16x32_bf16 v[64:67], v[160:163], v[218:221], v[64:67]
	v_mfma_f32_16x16x32_bf16 v[68:71], v[152:155], v[218:221], v[68:71]
	v_mfma_f32_16x16x32_bf16 v[68:71], v[148:151], v[214:217], v[68:71]
	s_barrier
	s_add_i32 s35, 0, 0x18000
	v_add_u32_e32 v136, s35, v165
	s_add_i32 s57, 0, 0x1c000
	ds_read_b128 v[148:151], v136
	ds_read_b128 v[152:155], v136 offset:1024
	ds_read_b128 v[156:159], v136 offset:2048
	ds_read_b128 v[160:163], v136 offset:3072
	v_add_u32_e32 v136, s57, v165
	ds_read_b128 v[174:177], v136
	ds_read_b128 v[178:181], v136 offset:1024
	ds_read_b128 v[182:185], v136 offset:2048
	ds_read_b128 v[186:189], v136 offset:3072
	s_add_u32 s28, s28, 0x100000
	s_addc_u32 s29, s29, 0
	s_mov_b32 m0, s43
	v_lshl_add_u64 v[190:191], s[28:29], 0, v[128:129]
	global_load_lds_dwordx4 v[190:191], off sc0
	v_lshl_add_u64 v[190:191], s[28:29], 0, v[132:133]
	s_mov_b32 m0, s44
	s_nop 0
	global_load_lds_dwordx4 v[190:191], off sc0
	ds_read_b128 v[190:193], v171 offset:32768
	ds_read_b128 v[194:197], v171 offset:33792
	ds_read_b128 v[198:201], v171 offset:34816
	ds_read_b128 v[202:205], v171 offset:35840
	ds_read_b128 v[206:209], v171 offset:36864
	ds_read_b128 v[210:213], v171 offset:37888
	ds_read_b128 v[214:217], v171 offset:38912
	ds_read_b128 v[218:221], v171 offset:39936
	s_waitcnt vmcnt(8)
	s_waitcnt lgkmcnt(0)
	s_barrier
	v_mfma_f32_16x16x32_bf16 v[124:127], v[148:151], v[190:193], v[124:127]
	v_mfma_f32_16x16x32_bf16 v[124:127], v[152:155], v[194:197], v[124:127]
	v_mfma_f32_16x16x32_bf16 v[120:123], v[160:163], v[194:197], v[120:123]
	v_mfma_f32_16x16x32_bf16 v[120:123], v[156:159], v[190:193], v[120:123]
	v_mfma_f32_16x16x32_bf16 v[60:63], v[174:177], v[190:193], v[60:63]
	v_mfma_f32_16x16x32_bf16 v[60:63], v[178:181], v[194:197], v[60:63]
	v_mfma_f32_16x16x32_bf16 v[56:59], v[186:189], v[194:197], v[56:59]
	v_mfma_f32_16x16x32_bf16 v[56:59], v[182:185], v[190:193], v[56:59]
	v_mfma_f32_16x16x32_bf16 v[48:51], v[182:185], v[198:201], v[48:51]
	v_mfma_f32_16x16x32_bf16 v[48:51], v[186:189], v[202:205], v[48:51]
	v_mfma_f32_16x16x32_bf16 v[52:55], v[178:181], v[202:205], v[52:55]
	v_mfma_f32_16x16x32_bf16 v[52:55], v[174:177], v[198:201], v[52:55]
	v_mfma_f32_16x16x32_bf16 v[112:115], v[156:159], v[198:201], v[112:115]
	v_mfma_f32_16x16x32_bf16 v[112:115], v[160:163], v[202:205], v[112:115]
	v_mfma_f32_16x16x32_bf16 v[116:119], v[152:155], v[202:205], v[116:119]
	v_mfma_f32_16x16x32_bf16 v[116:119], v[148:151], v[198:201], v[116:119]
	v_mfma_f32_16x16x32_bf16 v[108:111], v[148:151], v[206:209], v[108:111]
	v_mfma_f32_16x16x32_bf16 v[108:111], v[152:155], v[210:213], v[108:111]
	v_mfma_f32_16x16x32_bf16 v[104:107], v[160:163], v[210:213], v[104:107]
	v_mfma_f32_16x16x32_bf16 v[104:107], v[156:159], v[206:209], v[104:107]
	v_mfma_f32_16x16x32_bf16 v[44:47], v[174:177], v[206:209], v[44:47]
	v_mfma_f32_16x16x32_bf16 v[44:47], v[178:181], v[210:213], v[44:47]
	v_mfma_f32_16x16x32_bf16 v[40:43], v[186:189], v[210:213], v[40:43]
	v_mfma_f32_16x16x32_bf16 v[40:43], v[182:185], v[206:209], v[40:43]
	v_mfma_f32_16x16x32_bf16 v[32:35], v[182:185], v[214:217], v[32:35]
	v_mfma_f32_16x16x32_bf16 v[32:35], v[186:189], v[218:221], v[32:35]
	v_mfma_f32_16x16x32_bf16 v[36:39], v[178:181], v[218:221], v[36:39]
	v_mfma_f32_16x16x32_bf16 v[36:39], v[174:177], v[214:217], v[36:39]
	v_mfma_f32_16x16x32_bf16 v[96:99], v[156:159], v[214:217], v[96:99]
	v_mfma_f32_16x16x32_bf16 v[96:99], v[160:163], v[218:221], v[96:99]
	v_mfma_f32_16x16x32_bf16 v[100:103], v[152:155], v[218:221], v[100:103]
	v_mfma_f32_16x16x32_bf16 v[100:103], v[148:151], v[214:217], v[100:103]
	s_barrier
	s_add_i32 s28, s35, s36
	v_lshl_add_u64 v[190:191], v[222:223], 0, s[12:13]
	s_mov_b32 m0, s28
	s_nop 0
	global_load_lds_dwordx4 v[190:191], off sc0
	s_add_i32 m0, s28, 0x2000
	s_add_u32 s26, s26, 0x100800
	v_lshl_add_u64 v[190:191], v[224:225], 0, s[12:13]
	s_addc_u32 s27, s27, 0
	s_add_i32 s28, s57, s36
	global_load_lds_dwordx4 v[190:191], off sc0
	v_lshl_add_u64 v[190:191], s[26:27], 0, v[130:131]
	s_mov_b32 m0, s28
	s_nop 0
	global_load_lds_dwordx4 v[190:191], off sc0
	v_lshl_add_u64 v[190:191], s[26:27], 0, v[134:135]
	s_add_i32 m0, s28, 0x2000
	s_nop 0
	global_load_lds_dwordx4 v[190:191], off sc0
	v_lshl_add_u64 v[190:191], v[226:227], 0, s[12:13]
	s_mov_b32 m0, s49
	s_nop 0
	global_load_lds_dwordx4 v[190:191], off sc0
	v_lshl_add_u64 v[190:191], v[228:229], 0, s[12:13]
	s_mov_b32 m0, s50
	s_nop 0
	global_load_lds_dwordx4 v[190:191], off sc0
	ds_read_b128 v[190:193], v171 offset:49152
	ds_read_b128 v[194:197], v171 offset:50176
	ds_read_b128 v[198:201], v171 offset:51200
	ds_read_b128 v[202:205], v171 offset:52224
	ds_read_b128 v[206:209], v171 offset:53248
	ds_read_b128 v[210:213], v171 offset:54272
	ds_read_b128 v[214:217], v171 offset:55296
	ds_read_b128 v[218:221], v171 offset:56320
	s_waitcnt vmcnt(8)
	s_waitcnt lgkmcnt(0)
	s_barrier
	v_mfma_f32_16x16x32_bf16 v[92:95], v[148:151], v[190:193], v[92:95]
	v_mfma_f32_16x16x32_bf16 v[92:95], v[152:155], v[194:197], v[92:95]
	v_mfma_f32_16x16x32_bf16 v[88:91], v[160:163], v[194:197], v[88:91]
	v_mfma_f32_16x16x32_bf16 v[88:91], v[156:159], v[190:193], v[88:91]
	v_mfma_f32_16x16x32_bf16 v[28:31], v[174:177], v[190:193], v[28:31]
	v_mfma_f32_16x16x32_bf16 v[28:31], v[178:181], v[194:197], v[28:31]
	v_mfma_f32_16x16x32_bf16 v[24:27], v[186:189], v[194:197], v[24:27]
	v_mfma_f32_16x16x32_bf16 v[24:27], v[182:185], v[190:193], v[24:27]
	v_mfma_f32_16x16x32_bf16 v[16:19], v[182:185], v[198:201], v[16:19]
	v_mfma_f32_16x16x32_bf16 v[16:19], v[186:189], v[202:205], v[16:19]
	v_mfma_f32_16x16x32_bf16 v[20:23], v[178:181], v[202:205], v[20:23]
	v_mfma_f32_16x16x32_bf16 v[20:23], v[174:177], v[198:201], v[20:23]
	v_mfma_f32_16x16x32_bf16 v[80:83], v[156:159], v[198:201], v[80:83]
	v_mfma_f32_16x16x32_bf16 v[80:83], v[160:163], v[202:205], v[80:83]
	v_mfma_f32_16x16x32_bf16 v[84:87], v[152:155], v[202:205], v[84:87]
	v_mfma_f32_16x16x32_bf16 v[84:87], v[148:151], v[198:201], v[84:87]
	v_mfma_f32_16x16x32_bf16 v[76:79], v[148:151], v[206:209], v[76:79]
	v_mfma_f32_16x16x32_bf16 v[76:79], v[152:155], v[210:213], v[76:79]
	v_mfma_f32_16x16x32_bf16 v[72:75], v[160:163], v[210:213], v[72:75]
	v_mfma_f32_16x16x32_bf16 v[72:75], v[156:159], v[206:209], v[72:75]
	v_mfma_f32_16x16x32_bf16 v[12:15], v[174:177], v[206:209], v[12:15]
	v_mfma_f32_16x16x32_bf16 v[12:15], v[178:181], v[210:213], v[12:15]
	v_mfma_f32_16x16x32_bf16 v[8:11], v[186:189], v[210:213], v[8:11]
	v_mfma_f32_16x16x32_bf16 v[8:11], v[182:185], v[206:209], v[8:11]
	v_mfma_f32_16x16x32_bf16 v[0:3], v[182:185], v[214:217], v[0:3]
	v_mfma_f32_16x16x32_bf16 v[0:3], v[186:189], v[218:221], v[0:3]
	v_mfma_f32_16x16x32_bf16 v[4:7], v[178:181], v[218:221], v[4:7]
	v_mfma_f32_16x16x32_bf16 v[4:7], v[174:177], v[214:217], v[4:7]
	v_mfma_f32_16x16x32_bf16 v[64:67], v[156:159], v[214:217], v[64:67]
	v_mfma_f32_16x16x32_bf16 v[64:67], v[160:163], v[218:221], v[64:67]
	v_mfma_f32_16x16x32_bf16 v[68:71], v[152:155], v[218:221], v[68:71]
	v_mfma_f32_16x16x32_bf16 v[68:71], v[148:151], v[214:217], v[68:71]
	s_barrier
	s_add_i32 s34, s34, 2
	s_add_u32 s6, s6, 0x1000
	s_addc_u32 s7, s7, 0
	s_add_u32 s30, s30, 0x1000
	s_addc_u32 s31, s31, 0
	s_cmp_gt_u32 s34, 61
	s_cbranch_scc0 .LBB0_200

.LBB0_333:
	ds_read_b128 v[144:147], v152
	ds_read_b128 v[156:159], v152 offset:1024
	ds_read_b128 v[160:163], v152 offset:2048
	ds_read_b128 v[164:167], v152 offset:3072
	ds_read_b128 v[168:171], v153
	ds_read_b128 v[172:175], v153 offset:1024
	ds_read_b128 v[176:179], v153 offset:2048
	ds_read_b128 v[180:183], v153 offset:3072
	s_add_u32 s28, s24, 0x100
	s_addc_u32 s29, s25, 0
	s_cmp_eq_u32 s56, 60
	s_cselect_b32 s35, s13, s29
	s_cselect_b32 s34, s52, s28
	s_cselect_b32 s31, s11, s55
	s_cselect_b32 s30, s53, s54
	v_lshl_add_u64 v[184:185], s[24:25], 0, v[136:137]
	s_add_i32 m0, s21, 0xc000
	s_nop 0
	global_load_lds_dwordx4 v[184:185], off sc0
	v_lshl_add_u64 v[184:185], s[24:25], 0, v[138:139]
	s_add_i32 m0, s21, 0xe000
	s_nop 0
	global_load_lds_dwordx4 v[184:185], off sc0
	ds_read_b128 v[184:187], v154
	ds_read_b128 v[188:191], v154 offset:1024
	ds_read_b128 v[192:195], v154 offset:2048
	ds_read_b128 v[196:199], v154 offset:3072
	ds_read_b128 v[200:203], v154 offset:4096
	ds_read_b128 v[204:207], v154 offset:5120
	ds_read_b128 v[208:211], v154 offset:6144
	ds_read_b128 v[212:215], v154 offset:7168
	s_waitcnt vmcnt(8)
	s_waitcnt lgkmcnt(0)
	s_barrier
	v_mfma_f32_16x16x32_bf16 v[124:127], v[144:147], v[184:187], v[124:127]
	v_mfma_f32_16x16x32_bf16 v[124:127], v[156:159], v[188:191], v[124:127]
	v_mfma_f32_16x16x32_bf16 v[120:123], v[164:167], v[188:191], v[120:123]
	v_mfma_f32_16x16x32_bf16 v[120:123], v[160:163], v[184:187], v[120:123]
	v_mfma_f32_16x16x32_bf16 v[112:115], v[168:171], v[184:187], v[112:115]
	v_mfma_f32_16x16x32_bf16 v[112:115], v[172:175], v[188:191], v[112:115]
	v_mfma_f32_16x16x32_bf16 v[104:107], v[180:183], v[188:191], v[104:107]
	v_mfma_f32_16x16x32_bf16 v[104:107], v[176:179], v[184:187], v[104:107]
	v_mfma_f32_16x16x32_bf16 v[88:91], v[176:179], v[192:195], v[88:91]
	v_mfma_f32_16x16x32_bf16 v[88:91], v[180:183], v[196:199], v[88:91]
	v_mfma_f32_16x16x32_bf16 v[96:99], v[172:175], v[196:199], v[96:99]
	v_mfma_f32_16x16x32_bf16 v[96:99], v[168:171], v[192:195], v[96:99]
	v_mfma_f32_16x16x32_bf16 v[108:111], v[160:163], v[192:195], v[108:111]
	v_mfma_f32_16x16x32_bf16 v[108:111], v[164:167], v[196:199], v[108:111]
	v_mfma_f32_16x16x32_bf16 v[116:119], v[156:159], v[196:199], v[116:119]
	v_mfma_f32_16x16x32_bf16 v[116:119], v[144:147], v[192:195], v[116:119]
	v_mfma_f32_16x16x32_bf16 v[100:103], v[144:147], v[200:203], v[100:103]
	v_mfma_f32_16x16x32_bf16 v[100:103], v[156:159], v[204:207], v[100:103]
	v_mfma_f32_16x16x32_bf16 v[92:95], v[164:167], v[204:207], v[92:95]
	v_mfma_f32_16x16x32_bf16 v[92:95], v[160:163], v[200:203], v[92:95]
	v_mfma_f32_16x16x32_bf16 v[80:83], v[168:171], v[200:203], v[80:83]
	v_mfma_f32_16x16x32_bf16 v[80:83], v[172:175], v[204:207], v[80:83]
	v_mfma_f32_16x16x32_bf16 v[72:75], v[180:183], v[204:207], v[72:75]
	v_mfma_f32_16x16x32_bf16 v[72:75], v[176:179], v[200:203], v[72:75]
	v_mfma_f32_16x16x32_bf16 v[64:67], v[176:179], v[208:211], v[64:67]
	v_mfma_f32_16x16x32_bf16 v[64:67], v[180:183], v[212:215], v[64:67]
	v_mfma_f32_16x16x32_bf16 v[68:71], v[172:175], v[212:215], v[68:71]
	v_mfma_f32_16x16x32_bf16 v[68:71], v[168:171], v[208:211], v[68:71]
	v_mfma_f32_16x16x32_bf16 v[76:79], v[160:163], v[208:211], v[76:79]
	v_mfma_f32_16x16x32_bf16 v[76:79], v[164:167], v[212:215], v[76:79]
	v_mfma_f32_16x16x32_bf16 v[84:87], v[156:159], v[212:215], v[84:87]
	v_mfma_f32_16x16x32_bf16 v[84:87], v[144:147], v[208:211], v[84:87]
	s_barrier
	s_add_i32 s24, s49, s41
	v_lshl_add_u64 v[216:217], s[30:31], 0, v[130:131]
	s_mov_b32 m0, s24
	v_lshl_add_u64 v[218:219], s[30:31], 0, v[134:135]
	global_load_lds_dwordx4 v[216:217], off sc0
	s_add_i32 m0, s24, 0x2000
	s_add_u32 s24, s30, 0x100000
	s_addc_u32 s25, s31, 0
	s_add_i32 s57, s50, s41
	global_load_lds_dwordx4 v[218:219], off sc0
	v_lshl_add_u64 v[184:185], s[24:25], 0, v[130:131]
	s_mov_b32 m0, s57
	v_lshl_add_u64 v[220:221], s[34:35], 0, v[128:129]
	global_load_lds_dwordx4 v[184:185], off sc0
	v_lshl_add_u64 v[184:185], s[24:25], 0, v[134:135]
	s_add_i32 m0, s57, 0x2000
	v_lshl_add_u64 v[222:223], s[34:35], 0, v[132:133]
	global_load_lds_dwordx4 v[184:185], off sc0
	s_mov_b32 m0, s21
	s_nop 0
	global_load_lds_dwordx4 v[220:221], off sc0
	s_mov_b32 m0, s42
	s_nop 0
	global_load_lds_dwordx4 v[222:223], off sc0
	ds_read_b128 v[184:187], v154 offset:16384
	ds_read_b128 v[188:191], v154 offset:17408
	ds_read_b128 v[192:195], v154 offset:18432
	ds_read_b128 v[196:199], v154 offset:19456
	ds_read_b128 v[200:203], v154 offset:20480
	ds_read_b128 v[204:207], v154 offset:21504
	ds_read_b128 v[208:211], v154 offset:22528
	ds_read_b128 v[212:215], v154 offset:23552
	s_waitcnt vmcnt(8)
	s_waitcnt lgkmcnt(0)
	s_barrier
	v_mfma_f32_16x16x32_bf16 v[60:63], v[144:147], v[184:187], v[60:63]
	v_mfma_f32_16x16x32_bf16 v[60:63], v[156:159], v[188:191], v[60:63]
	v_mfma_f32_16x16x32_bf16 v[56:59], v[164:167], v[188:191], v[56:59]
	v_mfma_f32_16x16x32_bf16 v[56:59], v[160:163], v[184:187], v[56:59]
	v_mfma_f32_16x16x32_bf16 v[48:51], v[168:171], v[184:187], v[48:51]
	v_mfma_f32_16x16x32_bf16 v[48:51], v[172:175], v[188:191], v[48:51]
	v_mfma_f32_16x16x32_bf16 v[40:43], v[180:183], v[188:191], v[40:43]
	v_mfma_f32_16x16x32_bf16 v[40:43], v[176:179], v[184:187], v[40:43]
	v_mfma_f32_16x16x32_bf16 v[24:27], v[176:179], v[192:195], v[24:27]
	v_mfma_f32_16x16x32_bf16 v[24:27], v[180:183], v[196:199], v[24:27]
	v_mfma_f32_16x16x32_bf16 v[32:35], v[172:175], v[196:199], v[32:35]
	v_mfma_f32_16x16x32_bf16 v[32:35], v[168:171], v[192:195], v[32:35]
	v_mfma_f32_16x16x32_bf16 v[44:47], v[160:163], v[192:195], v[44:47]
	v_mfma_f32_16x16x32_bf16 v[44:47], v[164:167], v[196:199], v[44:47]
	v_mfma_f32_16x16x32_bf16 v[52:55], v[156:159], v[196:199], v[52:55]
	v_mfma_f32_16x16x32_bf16 v[52:55], v[144:147], v[192:195], v[52:55]
	v_mfma_f32_16x16x32_bf16 v[36:39], v[144:147], v[200:203], v[36:39]
	v_mfma_f32_16x16x32_bf16 v[36:39], v[156:159], v[204:207], v[36:39]
	v_mfma_f32_16x16x32_bf16 v[28:31], v[164:167], v[204:207], v[28:31]
	v_mfma_f32_16x16x32_bf16 v[28:31], v[160:163], v[200:203], v[28:31]
	v_mfma_f32_16x16x32_bf16 v[16:19], v[168:171], v[200:203], v[16:19]
	v_mfma_f32_16x16x32_bf16 v[16:19], v[172:175], v[204:207], v[16:19]
	v_mfma_f32_16x16x32_bf16 v[8:11], v[180:183], v[204:207], v[8:11]
	v_mfma_f32_16x16x32_bf16 v[8:11], v[176:179], v[200:203], v[8:11]
	v_mfma_f32_16x16x32_bf16 v[0:3], v[176:179], v[208:211], v[0:3]
	v_mfma_f32_16x16x32_bf16 v[0:3], v[180:183], v[212:215], v[0:3]
	v_mfma_f32_16x16x32_bf16 v[4:7], v[172:175], v[212:215], v[4:7]
	v_mfma_f32_16x16x32_bf16 v[4:7], v[168:171], v[208:211], v[4:7]
	v_mfma_f32_16x16x32_bf16 v[12:15], v[160:163], v[208:211], v[12:15]
	v_mfma_f32_16x16x32_bf16 v[12:15], v[164:167], v[212:215], v[12:15]
	v_mfma_f32_16x16x32_bf16 v[20:23], v[156:159], v[212:215], v[20:23]
	v_mfma_f32_16x16x32_bf16 v[20:23], v[144:147], v[208:211], v[20:23]
	s_barrier
	s_add_i32 s57, 0, 0x18000
	v_add_u32_e32 v155, s57, v149
	s_add_i32 s58, 0, 0x1c000
	ds_read_b128 v[144:147], v155
	ds_read_b128 v[156:159], v155 offset:1024
	ds_read_b128 v[160:163], v155 offset:2048
	ds_read_b128 v[164:167], v155 offset:3072
	v_add_u32_e32 v155, s58, v149
	ds_read_b128 v[168:171], v155
	ds_read_b128 v[172:175], v155 offset:1024
	ds_read_b128 v[176:179], v155 offset:2048
	ds_read_b128 v[180:183], v155 offset:3072
	s_add_u32 s24, s34, 0x100000
	s_addc_u32 s25, s35, 0
	s_mov_b32 m0, s43
	v_lshl_add_u64 v[184:185], s[24:25], 0, v[128:129]
	global_load_lds_dwordx4 v[184:185], off sc0
	v_lshl_add_u64 v[184:185], s[24:25], 0, v[132:133]
	s_mov_b32 m0, s44
	s_nop 0
	global_load_lds_dwordx4 v[184:185], off sc0
	ds_read_b128 v[184:187], v154 offset:32768
	ds_read_b128 v[188:191], v154 offset:33792
	ds_read_b128 v[192:195], v154 offset:34816
	ds_read_b128 v[196:199], v154 offset:35840
	ds_read_b128 v[200:203], v154 offset:36864
	ds_read_b128 v[204:207], v154 offset:37888
	ds_read_b128 v[208:211], v154 offset:38912
	ds_read_b128 v[212:215], v154 offset:39936
	s_waitcnt vmcnt(8)
	s_waitcnt lgkmcnt(0)
	s_barrier
	v_mfma_f32_16x16x32_bf16 v[124:127], v[144:147], v[184:187], v[124:127]
	v_mfma_f32_16x16x32_bf16 v[124:127], v[156:159], v[188:191], v[124:127]
	v_mfma_f32_16x16x32_bf16 v[120:123], v[164:167], v[188:191], v[120:123]
	v_mfma_f32_16x16x32_bf16 v[120:123], v[160:163], v[184:187], v[120:123]
	v_mfma_f32_16x16x32_bf16 v[112:115], v[168:171], v[184:187], v[112:115]
	v_mfma_f32_16x16x32_bf16 v[112:115], v[172:175], v[188:191], v[112:115]
	v_mfma_f32_16x16x32_bf16 v[104:107], v[180:183], v[188:191], v[104:107]
	v_mfma_f32_16x16x32_bf16 v[104:107], v[176:179], v[184:187], v[104:107]
	v_mfma_f32_16x16x32_bf16 v[88:91], v[176:179], v[192:195], v[88:91]
	v_mfma_f32_16x16x32_bf16 v[88:91], v[180:183], v[196:199], v[88:91]
	v_mfma_f32_16x16x32_bf16 v[96:99], v[172:175], v[196:199], v[96:99]
	v_mfma_f32_16x16x32_bf16 v[96:99], v[168:171], v[192:195], v[96:99]
	v_mfma_f32_16x16x32_bf16 v[108:111], v[160:163], v[192:195], v[108:111]
	v_mfma_f32_16x16x32_bf16 v[108:111], v[164:167], v[196:199], v[108:111]
	v_mfma_f32_16x16x32_bf16 v[116:119], v[156:159], v[196:199], v[116:119]
	v_mfma_f32_16x16x32_bf16 v[116:119], v[144:147], v[192:195], v[116:119]
	v_mfma_f32_16x16x32_bf16 v[100:103], v[144:147], v[200:203], v[100:103]
	v_mfma_f32_16x16x32_bf16 v[100:103], v[156:159], v[204:207], v[100:103]
	v_mfma_f32_16x16x32_bf16 v[92:95], v[164:167], v[204:207], v[92:95]
	v_mfma_f32_16x16x32_bf16 v[92:95], v[160:163], v[200:203], v[92:95]
	v_mfma_f32_16x16x32_bf16 v[80:83], v[168:171], v[200:203], v[80:83]
	v_mfma_f32_16x16x32_bf16 v[80:83], v[172:175], v[204:207], v[80:83]
	v_mfma_f32_16x16x32_bf16 v[72:75], v[180:183], v[204:207], v[72:75]
	v_mfma_f32_16x16x32_bf16 v[72:75], v[176:179], v[200:203], v[72:75]
	v_mfma_f32_16x16x32_bf16 v[64:67], v[176:179], v[208:211], v[64:67]
	v_mfma_f32_16x16x32_bf16 v[64:67], v[180:183], v[212:215], v[64:67]
	v_mfma_f32_16x16x32_bf16 v[68:71], v[172:175], v[212:215], v[68:71]
	v_mfma_f32_16x16x32_bf16 v[68:71], v[168:171], v[208:211], v[68:71]
	v_mfma_f32_16x16x32_bf16 v[76:79], v[160:163], v[208:211], v[76:79]
	v_mfma_f32_16x16x32_bf16 v[76:79], v[164:167], v[212:215], v[76:79]
	v_mfma_f32_16x16x32_bf16 v[84:87], v[156:159], v[212:215], v[84:87]
	v_mfma_f32_16x16x32_bf16 v[84:87], v[144:147], v[208:211], v[84:87]
	s_barrier
	s_add_i32 s24, s57, s41
	v_lshl_add_u64 v[184:185], v[216:217], 0, s[8:9]
	s_mov_b32 m0, s24
	s_nop 0
	global_load_lds_dwordx4 v[184:185], off sc0
	s_add_i32 m0, s24, 0x2000
	s_add_u32 s24, s30, 0x100080
	v_lshl_add_u64 v[184:185], v[218:219], 0, s[8:9]
	s_addc_u32 s25, s31, 0
	s_add_i32 s30, s58, s41
	global_load_lds_dwordx4 v[184:185], off sc0
	v_lshl_add_u64 v[184:185], s[24:25], 0, v[130:131]
	s_mov_b32 m0, s30
	s_nop 0
	global_load_lds_dwordx4 v[184:185], off sc0
	v_lshl_add_u64 v[184:185], s[24:25], 0, v[134:135]
	s_add_i32 m0, s30, 0x2000
	s_nop 0
	global_load_lds_dwordx4 v[184:185], off sc0
	v_lshl_add_u64 v[184:185], v[220:221], 0, s[8:9]
	s_mov_b32 m0, s46
	s_nop 0
	global_load_lds_dwordx4 v[184:185], off sc0
	v_lshl_add_u64 v[184:185], v[222:223], 0, s[8:9]
	s_mov_b32 m0, s47
	s_nop 0
	global_load_lds_dwordx4 v[184:185], off sc0
	ds_read_b128 v[184:187], v154 offset:49152
	ds_read_b128 v[188:191], v154 offset:50176
	ds_read_b128 v[192:195], v154 offset:51200
	ds_read_b128 v[196:199], v154 offset:52224
	ds_read_b128 v[200:203], v154 offset:53248
	ds_read_b128 v[204:207], v154 offset:54272
	ds_read_b128 v[208:211], v154 offset:55296
	ds_read_b128 v[212:215], v154 offset:56320
	s_waitcnt vmcnt(8)
	s_waitcnt lgkmcnt(0)
	s_barrier
	v_mfma_f32_16x16x32_bf16 v[60:63], v[144:147], v[184:187], v[60:63]
	v_mfma_f32_16x16x32_bf16 v[60:63], v[156:159], v[188:191], v[60:63]
	v_mfma_f32_16x16x32_bf16 v[56:59], v[164:167], v[188:191], v[56:59]
	v_mfma_f32_16x16x32_bf16 v[56:59], v[160:163], v[184:187], v[56:59]
	v_mfma_f32_16x16x32_bf16 v[48:51], v[168:171], v[184:187], v[48:51]
	v_mfma_f32_16x16x32_bf16 v[48:51], v[172:175], v[188:191], v[48:51]
	v_mfma_f32_16x16x32_bf16 v[40:43], v[180:183], v[188:191], v[40:43]
	v_mfma_f32_16x16x32_bf16 v[40:43], v[176:179], v[184:187], v[40:43]
	v_mfma_f32_16x16x32_bf16 v[24:27], v[176:179], v[192:195], v[24:27]
	v_mfma_f32_16x16x32_bf16 v[24:27], v[180:183], v[196:199], v[24:27]
	v_mfma_f32_16x16x32_bf16 v[32:35], v[172:175], v[196:199], v[32:35]
	v_mfma_f32_16x16x32_bf16 v[32:35], v[168:171], v[192:195], v[32:35]
	v_mfma_f32_16x16x32_bf16 v[44:47], v[160:163], v[192:195], v[44:47]
	v_mfma_f32_16x16x32_bf16 v[44:47], v[164:167], v[196:199], v[44:47]
	v_mfma_f32_16x16x32_bf16 v[52:55], v[156:159], v[196:199], v[52:55]
	v_mfma_f32_16x16x32_bf16 v[52:55], v[144:147], v[192:195], v[52:55]
	v_mfma_f32_16x16x32_bf16 v[36:39], v[144:147], v[200:203], v[36:39]
	v_mfma_f32_16x16x32_bf16 v[36:39], v[156:159], v[204:207], v[36:39]
	v_mfma_f32_16x16x32_bf16 v[28:31], v[164:167], v[204:207], v[28:31]
	v_mfma_f32_16x16x32_bf16 v[28:31], v[160:163], v[200:203], v[28:31]
	v_mfma_f32_16x16x32_bf16 v[16:19], v[168:171], v[200:203], v[16:19]
	v_mfma_f32_16x16x32_bf16 v[16:19], v[172:175], v[204:207], v[16:19]
	v_mfma_f32_16x16x32_bf16 v[8:11], v[180:183], v[204:207], v[8:11]
	v_mfma_f32_16x16x32_bf16 v[8:11], v[176:179], v[200:203], v[8:11]
	v_mfma_f32_16x16x32_bf16 v[0:3], v[176:179], v[208:211], v[0:3]
	v_mfma_f32_16x16x32_bf16 v[0:3], v[180:183], v[212:215], v[0:3]
	v_mfma_f32_16x16x32_bf16 v[4:7], v[172:175], v[212:215], v[4:7]
	v_mfma_f32_16x16x32_bf16 v[4:7], v[168:171], v[208:211], v[4:7]
	v_mfma_f32_16x16x32_bf16 v[12:15], v[160:163], v[208:211], v[12:15]
	v_mfma_f32_16x16x32_bf16 v[12:15], v[164:167], v[212:215], v[12:15]
	v_mfma_f32_16x16x32_bf16 v[20:23], v[156:159], v[212:215], v[20:23]
	v_mfma_f32_16x16x32_bf16 v[20:23], v[144:147], v[208:211], v[20:23]
	s_barrier
	s_add_i32 s56, s56, 2
	s_add_u32 s54, s54, 0x100
	s_addc_u32 s55, s55, 0
	s_cmp_gt_u32 s56, 61
	s_mov_b64 s[24:25], s[28:29]
	s_cbranch_scc0 .LBB0_333
	s_and_b64 vcc, exec, s[0:1]
	s_cbranch_vccz .LBB0_336
	s_barrier

.LBB0_1202:
	ds_read_b128 v[128:131], v176
	ds_read_b128 v[132:135], v176 offset:1024
	ds_read_b128 v[136:139], v176 offset:2048
	ds_read_b128 v[140:143], v176 offset:3072
	ds_read_b128 v[144:147], v177
	ds_read_b128 v[148:151], v177 offset:1024
	ds_read_b128 v[180:183], v177 offset:2048
	ds_read_b128 v[184:187], v177 offset:3072
	s_add_u32 s30, s28, 0xfff00080
	s_addc_u32 s31, s29, -1
	s_cmp_eq_u32 s40, 60
	s_cselect_b32 s35, s23, s31
	s_cselect_b32 s34, s36, s30
	s_cselect_b32 s31, s21, s39
	s_cselect_b32 s30, s37, s38
	v_lshl_add_u64 v[172:173], s[28:29], 0, v[164:165]
	s_add_i32 m0, s7, 0xc000
	s_nop 0
	global_load_lds_dwordx4 v[172:173], off sc0
	v_lshl_add_u64 v[172:173], s[28:29], 0, v[166:167]
	s_add_i32 m0, s7, 0xe000
	s_nop 0
	global_load_lds_dwordx4 v[172:173], off sc0
	ds_read_b128 v[188:191], v178
	ds_read_b128 v[192:195], v178 offset:1024
	ds_read_b128 v[196:199], v178 offset:2048
	ds_read_b128 v[200:203], v178 offset:3072
	ds_read_b128 v[204:207], v178 offset:4096
	ds_read_b128 v[208:211], v178 offset:5120
	ds_read_b128 v[212:215], v178 offset:6144
	ds_read_b128 v[216:219], v178 offset:7168
	s_waitcnt vmcnt(8)
	s_waitcnt lgkmcnt(0)
	s_barrier
	v_mfma_f32_16x16x32_bf16 v[124:127], v[128:131], v[188:191], v[124:127]
	v_mfma_f32_16x16x32_bf16 v[124:127], v[132:135], v[192:195], v[124:127]
	v_mfma_f32_16x16x32_bf16 v[120:123], v[140:143], v[192:195], v[120:123]
	v_mfma_f32_16x16x32_bf16 v[120:123], v[136:139], v[188:191], v[120:123]
	v_mfma_f32_16x16x32_bf16 v[116:119], v[144:147], v[188:191], v[116:119]
	v_mfma_f32_16x16x32_bf16 v[116:119], v[148:151], v[192:195], v[116:119]
	v_mfma_f32_16x16x32_bf16 v[112:115], v[184:187], v[192:195], v[112:115]
	v_mfma_f32_16x16x32_bf16 v[112:115], v[180:183], v[188:191], v[112:115]
	v_mfma_f32_16x16x32_bf16 v[96:99], v[180:183], v[196:199], v[96:99]
	v_mfma_f32_16x16x32_bf16 v[96:99], v[184:187], v[200:203], v[96:99]
	v_mfma_f32_16x16x32_bf16 v[100:103], v[148:151], v[200:203], v[100:103]
	v_mfma_f32_16x16x32_bf16 v[100:103], v[144:147], v[196:199], v[100:103]
	v_mfma_f32_16x16x32_bf16 v[104:107], v[136:139], v[196:199], v[104:107]
	v_mfma_f32_16x16x32_bf16 v[104:107], v[140:143], v[200:203], v[104:107]
	v_mfma_f32_16x16x32_bf16 v[108:111], v[132:135], v[200:203], v[108:111]
	v_mfma_f32_16x16x32_bf16 v[108:111], v[128:131], v[196:199], v[108:111]
	v_mfma_f32_16x16x32_bf16 v[92:95], v[128:131], v[204:207], v[92:95]
	v_mfma_f32_16x16x32_bf16 v[92:95], v[132:135], v[208:211], v[92:95]
	v_mfma_f32_16x16x32_bf16 v[88:91], v[140:143], v[208:211], v[88:91]
	v_mfma_f32_16x16x32_bf16 v[88:91], v[136:139], v[204:207], v[88:91]
	v_mfma_f32_16x16x32_bf16 v[84:87], v[144:147], v[204:207], v[84:87]
	v_mfma_f32_16x16x32_bf16 v[84:87], v[148:151], v[208:211], v[84:87]
	v_mfma_f32_16x16x32_bf16 v[80:83], v[184:187], v[208:211], v[80:83]
	v_mfma_f32_16x16x32_bf16 v[80:83], v[180:183], v[204:207], v[80:83]
	v_mfma_f32_16x16x32_bf16 v[64:67], v[180:183], v[212:215], v[64:67]
	v_mfma_f32_16x16x32_bf16 v[64:67], v[184:187], v[216:219], v[64:67]
	v_mfma_f32_16x16x32_bf16 v[68:71], v[148:151], v[216:219], v[68:71]
	v_mfma_f32_16x16x32_bf16 v[68:71], v[144:147], v[212:215], v[68:71]
	v_mfma_f32_16x16x32_bf16 v[72:75], v[136:139], v[212:215], v[72:75]
	v_mfma_f32_16x16x32_bf16 v[72:75], v[140:143], v[216:219], v[72:75]
	v_mfma_f32_16x16x32_bf16 v[76:79], v[132:135], v[216:219], v[76:79]
	v_mfma_f32_16x16x32_bf16 v[76:79], v[128:131], v[212:215], v[76:79]
	s_barrier
	s_add_i32 s41, s68, s33
	v_lshl_add_u64 v[172:173], s[30:31], 0, v[154:155]
	s_mov_b32 m0, s41
	v_lshl_add_u64 v[220:221], s[30:31], 0, v[158:159]
	global_load_lds_dwordx4 v[172:173], off sc0
	s_add_i32 m0, s41, 0x2000
	s_add_u32 s42, s30, 0x100000
	s_addc_u32 s43, s31, 0
	s_add_i32 s41, s69, s33
	global_load_lds_dwordx4 v[220:221], off sc0
	v_lshl_add_u64 v[188:189], s[42:43], 0, v[154:155]
	s_mov_b32 m0, s41
	v_lshl_add_u64 v[222:223], s[34:35], 0, v[152:153]
	global_load_lds_dwordx4 v[188:189], off sc0
	v_lshl_add_u64 v[188:189], s[42:43], 0, v[158:159]
	s_add_i32 m0, s41, 0x2000
	v_lshl_add_u64 v[224:225], s[34:35], 0, v[156:157]
	global_load_lds_dwordx4 v[188:189], off sc0
	s_mov_b32 m0, s7
	s_nop 0
	global_load_lds_dwordx4 v[222:223], off sc0
	s_mov_b32 m0, s59
	s_nop 0
	global_load_lds_dwordx4 v[224:225], off sc0
	ds_read_b128 v[188:191], v178 offset:16384
	ds_read_b128 v[192:195], v178 offset:17408
	ds_read_b128 v[196:199], v178 offset:18432
	ds_read_b128 v[200:203], v178 offset:19456
	ds_read_b128 v[204:207], v178 offset:20480
	ds_read_b128 v[208:211], v178 offset:21504
	ds_read_b128 v[212:215], v178 offset:22528
	ds_read_b128 v[216:219], v178 offset:23552
	s_waitcnt vmcnt(8)
	s_waitcnt lgkmcnt(0)
	s_barrier
	v_mfma_f32_16x16x32_bf16 v[60:63], v[128:131], v[188:191], v[60:63]
	v_mfma_f32_16x16x32_bf16 v[60:63], v[132:135], v[192:195], v[60:63]
	v_mfma_f32_16x16x32_bf16 v[56:59], v[140:143], v[192:195], v[56:59]
	v_mfma_f32_16x16x32_bf16 v[56:59], v[136:139], v[188:191], v[56:59]
	v_mfma_f32_16x16x32_bf16 v[52:55], v[144:147], v[188:191], v[52:55]
	v_mfma_f32_16x16x32_bf16 v[52:55], v[148:151], v[192:195], v[52:55]
	v_mfma_f32_16x16x32_bf16 v[48:51], v[184:187], v[192:195], v[48:51]
	v_mfma_f32_16x16x32_bf16 v[48:51], v[180:183], v[188:191], v[48:51]
	v_mfma_f32_16x16x32_bf16 v[32:35], v[180:183], v[196:199], v[32:35]
	v_mfma_f32_16x16x32_bf16 v[32:35], v[184:187], v[200:203], v[32:35]
	v_mfma_f32_16x16x32_bf16 v[36:39], v[148:151], v[200:203], v[36:39]
	v_mfma_f32_16x16x32_bf16 v[36:39], v[144:147], v[196:199], v[36:39]
	v_mfma_f32_16x16x32_bf16 v[40:43], v[136:139], v[196:199], v[40:43]
	v_mfma_f32_16x16x32_bf16 v[40:43], v[140:143], v[200:203], v[40:43]
	v_mfma_f32_16x16x32_bf16 v[44:47], v[132:135], v[200:203], v[44:47]
	v_mfma_f32_16x16x32_bf16 v[44:47], v[128:131], v[196:199], v[44:47]
	v_mfma_f32_16x16x32_bf16 v[28:31], v[128:131], v[204:207], v[28:31]
	v_mfma_f32_16x16x32_bf16 v[28:31], v[132:135], v[208:211], v[28:31]
	v_mfma_f32_16x16x32_bf16 v[24:27], v[140:143], v[208:211], v[24:27]
	v_mfma_f32_16x16x32_bf16 v[24:27], v[136:139], v[204:207], v[24:27]
	v_mfma_f32_16x16x32_bf16 v[20:23], v[144:147], v[204:207], v[20:23]
	v_mfma_f32_16x16x32_bf16 v[20:23], v[148:151], v[208:211], v[20:23]
	v_mfma_f32_16x16x32_bf16 v[16:19], v[184:187], v[208:211], v[16:19]
	v_mfma_f32_16x16x32_bf16 v[16:19], v[180:183], v[204:207], v[16:19]
	v_mfma_f32_16x16x32_bf16 v[0:3], v[180:183], v[212:215], v[0:3]
	v_mfma_f32_16x16x32_bf16 v[0:3], v[184:187], v[216:219], v[0:3]
	v_mfma_f32_16x16x32_bf16 v[4:7], v[148:151], v[216:219], v[4:7]
	v_mfma_f32_16x16x32_bf16 v[4:7], v[144:147], v[212:215], v[4:7]
	v_mfma_f32_16x16x32_bf16 v[8:11], v[136:139], v[212:215], v[8:11]
	v_mfma_f32_16x16x32_bf16 v[8:11], v[140:143], v[216:219], v[8:11]
	v_mfma_f32_16x16x32_bf16 v[12:15], v[132:135], v[216:219], v[12:15]
	v_mfma_f32_16x16x32_bf16 v[12:15], v[128:131], v[212:215], v[12:15]
	s_barrier
	s_add_i32 s41, 0, 0x18000
	s_add_i32 s42, 0, 0x1c000
	v_add_u32_e32 v140, s41, v174
	v_add_u32_e32 v184, s42, v174
	ds_read_b128 v[128:131], v140
	ds_read_b128 v[132:135], v140 offset:1024
	ds_read_b128 v[136:139], v140 offset:2048
	ds_read_b128 v[140:143], v140 offset:3072
	ds_read_b128 v[144:147], v184
	ds_read_b128 v[148:151], v184 offset:1024
	ds_read_b128 v[180:183], v184 offset:2048
	ds_read_b128 v[184:187], v184 offset:3072
	s_add_u32 s34, s34, 0x100000
	s_addc_u32 s35, s35, 0
	s_mov_b32 m0, s60
	v_lshl_add_u64 v[188:189], s[34:35], 0, v[152:153]
	global_load_lds_dwordx4 v[188:189], off sc0
	v_lshl_add_u64 v[188:189], s[34:35], 0, v[156:157]
	s_mov_b32 m0, s61
	s_nop 0
	global_load_lds_dwordx4 v[188:189], off sc0
	ds_read_b128 v[188:191], v178 offset:32768
	ds_read_b128 v[192:195], v178 offset:33792
	ds_read_b128 v[196:199], v178 offset:34816
	ds_read_b128 v[200:203], v178 offset:35840
	ds_read_b128 v[204:207], v178 offset:36864
	ds_read_b128 v[208:211], v178 offset:37888
	ds_read_b128 v[212:215], v178 offset:38912
	ds_read_b128 v[216:219], v178 offset:39936
	s_waitcnt vmcnt(8)
	s_waitcnt lgkmcnt(0)
	s_barrier
	v_mfma_f32_16x16x32_bf16 v[124:127], v[128:131], v[188:191], v[124:127]
	v_mfma_f32_16x16x32_bf16 v[124:127], v[132:135], v[192:195], v[124:127]
	v_mfma_f32_16x16x32_bf16 v[120:123], v[140:143], v[192:195], v[120:123]
	v_mfma_f32_16x16x32_bf16 v[120:123], v[136:139], v[188:191], v[120:123]
	v_mfma_f32_16x16x32_bf16 v[116:119], v[144:147], v[188:191], v[116:119]
	v_mfma_f32_16x16x32_bf16 v[116:119], v[148:151], v[192:195], v[116:119]
	v_mfma_f32_16x16x32_bf16 v[112:115], v[184:187], v[192:195], v[112:115]
	v_mfma_f32_16x16x32_bf16 v[112:115], v[180:183], v[188:191], v[112:115]
	v_mfma_f32_16x16x32_bf16 v[96:99], v[180:183], v[196:199], v[96:99]
	v_mfma_f32_16x16x32_bf16 v[96:99], v[184:187], v[200:203], v[96:99]
	v_mfma_f32_16x16x32_bf16 v[100:103], v[148:151], v[200:203], v[100:103]
	v_mfma_f32_16x16x32_bf16 v[100:103], v[144:147], v[196:199], v[100:103]
	v_mfma_f32_16x16x32_bf16 v[104:107], v[136:139], v[196:199], v[104:107]
	v_mfma_f32_16x16x32_bf16 v[104:107], v[140:143], v[200:203], v[104:107]
	v_mfma_f32_16x16x32_bf16 v[108:111], v[132:135], v[200:203], v[108:111]
	v_mfma_f32_16x16x32_bf16 v[108:111], v[128:131], v[196:199], v[108:111]
	v_mfma_f32_16x16x32_bf16 v[92:95], v[128:131], v[204:207], v[92:95]
	v_mfma_f32_16x16x32_bf16 v[92:95], v[132:135], v[208:211], v[92:95]
	v_mfma_f32_16x16x32_bf16 v[88:91], v[140:143], v[208:211], v[88:91]
	v_mfma_f32_16x16x32_bf16 v[88:91], v[136:139], v[204:207], v[88:91]
	v_mfma_f32_16x16x32_bf16 v[84:87], v[144:147], v[204:207], v[84:87]
	v_mfma_f32_16x16x32_bf16 v[84:87], v[148:151], v[208:211], v[84:87]
	v_mfma_f32_16x16x32_bf16 v[80:83], v[184:187], v[208:211], v[80:83]
	v_mfma_f32_16x16x32_bf16 v[80:83], v[180:183], v[204:207], v[80:83]
	v_mfma_f32_16x16x32_bf16 v[64:67], v[180:183], v[212:215], v[64:67]
	v_mfma_f32_16x16x32_bf16 v[64:67], v[184:187], v[216:219], v[64:67]
	v_mfma_f32_16x16x32_bf16 v[68:71], v[148:151], v[216:219], v[68:71]
	v_mfma_f32_16x16x32_bf16 v[68:71], v[144:147], v[212:215], v[68:71]
	v_mfma_f32_16x16x32_bf16 v[72:75], v[136:139], v[212:215], v[72:75]
	v_mfma_f32_16x16x32_bf16 v[72:75], v[140:143], v[216:219], v[72:75]
	v_mfma_f32_16x16x32_bf16 v[76:79], v[132:135], v[216:219], v[76:79]
	v_mfma_f32_16x16x32_bf16 v[76:79], v[128:131], v[212:215], v[76:79]
	s_barrier
	s_add_i32 s34, s41, s33
	v_lshl_add_u64 v[172:173], v[172:173], 0, s[16:17]
	s_mov_b32 m0, s34
	s_nop 0
	global_load_lds_dwordx4 v[172:173], off sc0
	s_add_i32 m0, s34, 0x2000
	s_add_u32 s30, s30, 0x100800
	v_lshl_add_u64 v[172:173], v[220:221], 0, s[16:17]
	s_addc_u32 s31, s31, 0
	s_add_i32 s34, s42, s33
	global_load_lds_dwordx4 v[172:173], off sc0
	v_lshl_add_u64 v[172:173], s[30:31], 0, v[154:155]
	s_mov_b32 m0, s34
	s_nop 0
	global_load_lds_dwordx4 v[172:173], off sc0
	v_lshl_add_u64 v[172:173], s[30:31], 0, v[158:159]
	s_add_i32 m0, s34, 0x2000
	s_nop 0
	global_load_lds_dwordx4 v[172:173], off sc0
	v_lshl_add_u64 v[172:173], v[222:223], 0, s[18:19]
	s_mov_b32 m0, s63
	s_nop 0
	global_load_lds_dwordx4 v[172:173], off sc0
	v_lshl_add_u64 v[172:173], v[224:225], 0, s[18:19]
	s_mov_b32 m0, s64
	s_nop 0
	global_load_lds_dwordx4 v[172:173], off sc0
	ds_read_b128 v[188:191], v178 offset:49152
	ds_read_b128 v[192:195], v178 offset:50176
	ds_read_b128 v[196:199], v178 offset:51200
	ds_read_b128 v[200:203], v178 offset:52224
	ds_read_b128 v[204:207], v178 offset:53248
	ds_read_b128 v[208:211], v178 offset:54272
	ds_read_b128 v[212:215], v178 offset:55296
	ds_read_b128 v[216:219], v178 offset:56320
	s_waitcnt vmcnt(8)
	s_waitcnt lgkmcnt(0)
	s_barrier
	v_mfma_f32_16x16x32_bf16 v[60:63], v[128:131], v[188:191], v[60:63]
	v_mfma_f32_16x16x32_bf16 v[60:63], v[132:135], v[192:195], v[60:63]
	v_mfma_f32_16x16x32_bf16 v[56:59], v[140:143], v[192:195], v[56:59]
	v_mfma_f32_16x16x32_bf16 v[56:59], v[136:139], v[188:191], v[56:59]
	v_mfma_f32_16x16x32_bf16 v[52:55], v[144:147], v[188:191], v[52:55]
	v_mfma_f32_16x16x32_bf16 v[52:55], v[148:151], v[192:195], v[52:55]
	v_mfma_f32_16x16x32_bf16 v[48:51], v[184:187], v[192:195], v[48:51]
	v_mfma_f32_16x16x32_bf16 v[48:51], v[180:183], v[188:191], v[48:51]
	v_mfma_f32_16x16x32_bf16 v[32:35], v[180:183], v[196:199], v[32:35]
	v_mfma_f32_16x16x32_bf16 v[32:35], v[184:187], v[200:203], v[32:35]
	v_mfma_f32_16x16x32_bf16 v[36:39], v[148:151], v[200:203], v[36:39]
	v_mfma_f32_16x16x32_bf16 v[36:39], v[144:147], v[196:199], v[36:39]
	v_mfma_f32_16x16x32_bf16 v[40:43], v[136:139], v[196:199], v[40:43]
	v_mfma_f32_16x16x32_bf16 v[40:43], v[140:143], v[200:203], v[40:43]
	v_mfma_f32_16x16x32_bf16 v[44:47], v[132:135], v[200:203], v[44:47]
	v_mfma_f32_16x16x32_bf16 v[44:47], v[128:131], v[196:199], v[44:47]
	v_mfma_f32_16x16x32_bf16 v[28:31], v[128:131], v[204:207], v[28:31]
	v_mfma_f32_16x16x32_bf16 v[28:31], v[132:135], v[208:211], v[28:31]
	v_mfma_f32_16x16x32_bf16 v[24:27], v[140:143], v[208:211], v[24:27]
	v_mfma_f32_16x16x32_bf16 v[24:27], v[136:139], v[204:207], v[24:27]
	v_mfma_f32_16x16x32_bf16 v[20:23], v[144:147], v[204:207], v[20:23]
	v_mfma_f32_16x16x32_bf16 v[20:23], v[148:151], v[208:211], v[20:23]
	v_mfma_f32_16x16x32_bf16 v[16:19], v[184:187], v[208:211], v[16:19]
	v_mfma_f32_16x16x32_bf16 v[16:19], v[180:183], v[204:207], v[16:19]
	v_mfma_f32_16x16x32_bf16 v[0:3], v[180:183], v[212:215], v[0:3]
	v_mfma_f32_16x16x32_bf16 v[0:3], v[184:187], v[216:219], v[0:3]
	v_mfma_f32_16x16x32_bf16 v[4:7], v[148:151], v[216:219], v[4:7]
	v_mfma_f32_16x16x32_bf16 v[4:7], v[144:147], v[212:215], v[4:7]
	v_mfma_f32_16x16x32_bf16 v[8:11], v[136:139], v[212:215], v[8:11]
	v_mfma_f32_16x16x32_bf16 v[8:11], v[140:143], v[216:219], v[8:11]
	v_mfma_f32_16x16x32_bf16 v[12:15], v[132:135], v[216:219], v[12:15]
	v_mfma_f32_16x16x32_bf16 v[12:15], v[128:131], v[212:215], v[12:15]
	s_barrier
	s_add_i32 s40, s40, 2
	s_add_u32 s38, s38, 0x1000
	s_addc_u32 s39, s39, 0
	s_add_u32 s28, s28, 0x100
	s_addc_u32 s29, s29, 0
	s_cmp_gt_u32 s40, 61
	s_cbranch_scc0 .LBB0_1202

.LBB0_1263:
	ds_read_b128 v[146:149], v152
	ds_read_b128 v[156:159], v152 offset:1024
	ds_read_b128 v[160:163], v152 offset:2048
	ds_read_b128 v[164:167], v152 offset:3072
	ds_read_b128 v[168:171], v153
	ds_read_b128 v[172:175], v153 offset:1024
	ds_read_b128 v[176:179], v153 offset:2048
	ds_read_b128 v[180:183], v153 offset:3072
	s_add_u32 s22, s20, 0x100
	s_addc_u32 s23, s21, 0
	s_cmp_eq_u32 s46, 12
	s_cselect_b32 s27, s5, s23
	s_cselect_b32 s26, s4, s22
	s_cselect_b32 s25, s19, s15
	s_cselect_b32 s24, s18, s6
	v_lshl_add_u64 v[184:185], s[20:21], 0, v[136:137]
	s_add_i32 m0, s17, 0xc000
	s_nop 0
	global_load_lds_dwordx4 v[184:185], off sc0
	v_lshl_add_u64 v[184:185], s[20:21], 0, v[138:139]
	s_add_i32 m0, s17, 0xe000
	s_nop 0
	global_load_lds_dwordx4 v[184:185], off sc0
	ds_read_b128 v[184:187], v154
	ds_read_b128 v[188:191], v154 offset:1024
	ds_read_b128 v[192:195], v154 offset:2048
	ds_read_b128 v[196:199], v154 offset:3072
	ds_read_b128 v[200:203], v154 offset:4096
	ds_read_b128 v[204:207], v154 offset:5120
	ds_read_b128 v[208:211], v154 offset:6144
	ds_read_b128 v[212:215], v154 offset:7168
	s_waitcnt vmcnt(8)
	s_waitcnt lgkmcnt(0)
	s_barrier
	v_mfma_f32_16x16x32_bf16 v[124:127], v[146:149], v[184:187], v[124:127]
	v_mfma_f32_16x16x32_bf16 v[124:127], v[156:159], v[188:191], v[124:127]
	v_mfma_f32_16x16x32_bf16 v[120:123], v[164:167], v[188:191], v[120:123]
	v_mfma_f32_16x16x32_bf16 v[120:123], v[160:163], v[184:187], v[120:123]
	v_mfma_f32_16x16x32_bf16 v[116:119], v[168:171], v[184:187], v[116:119]
	v_mfma_f32_16x16x32_bf16 v[116:119], v[172:175], v[188:191], v[116:119]
	v_mfma_f32_16x16x32_bf16 v[108:111], v[180:183], v[188:191], v[108:111]
	v_mfma_f32_16x16x32_bf16 v[108:111], v[176:179], v[184:187], v[108:111]
	v_mfma_f32_16x16x32_bf16 v[92:95], v[176:179], v[192:195], v[92:95]
	v_mfma_f32_16x16x32_bf16 v[92:95], v[180:183], v[196:199], v[92:95]
	v_mfma_f32_16x16x32_bf16 v[100:103], v[172:175], v[196:199], v[100:103]
	v_mfma_f32_16x16x32_bf16 v[100:103], v[168:171], v[192:195], v[100:103]
	v_mfma_f32_16x16x32_bf16 v[104:107], v[160:163], v[192:195], v[104:107]
	v_mfma_f32_16x16x32_bf16 v[104:107], v[164:167], v[196:199], v[104:107]
	v_mfma_f32_16x16x32_bf16 v[112:115], v[156:159], v[196:199], v[112:115]
	v_mfma_f32_16x16x32_bf16 v[112:115], v[146:149], v[192:195], v[112:115]
	v_mfma_f32_16x16x32_bf16 v[96:99], v[146:149], v[200:203], v[96:99]
	v_mfma_f32_16x16x32_bf16 v[96:99], v[156:159], v[204:207], v[96:99]
	v_mfma_f32_16x16x32_bf16 v[88:91], v[164:167], v[204:207], v[88:91]
	v_mfma_f32_16x16x32_bf16 v[88:91], v[160:163], v[200:203], v[88:91]
	v_mfma_f32_16x16x32_bf16 v[84:87], v[168:171], v[200:203], v[84:87]
	v_mfma_f32_16x16x32_bf16 v[84:87], v[172:175], v[204:207], v[84:87]
	v_mfma_f32_16x16x32_bf16 v[76:79], v[180:183], v[204:207], v[76:79]
	v_mfma_f32_16x16x32_bf16 v[76:79], v[176:179], v[200:203], v[76:79]
	v_mfma_f32_16x16x32_bf16 v[64:67], v[176:179], v[208:211], v[64:67]
	v_mfma_f32_16x16x32_bf16 v[64:67], v[180:183], v[212:215], v[64:67]
	v_mfma_f32_16x16x32_bf16 v[68:71], v[172:175], v[212:215], v[68:71]
	v_mfma_f32_16x16x32_bf16 v[68:71], v[168:171], v[208:211], v[68:71]
	v_mfma_f32_16x16x32_bf16 v[72:75], v[160:163], v[208:211], v[72:75]
	v_mfma_f32_16x16x32_bf16 v[72:75], v[164:167], v[212:215], v[72:75]
	v_mfma_f32_16x16x32_bf16 v[80:83], v[156:159], v[212:215], v[80:83]
	v_mfma_f32_16x16x32_bf16 v[80:83], v[146:149], v[208:211], v[80:83]
	s_barrier
	s_add_i32 s20, s41, s33
	v_lshl_add_u64 v[216:217], s[24:25], 0, v[130:131]
	s_mov_b32 m0, s20
	v_lshl_add_u64 v[218:219], s[24:25], 0, v[134:135]
	global_load_lds_dwordx4 v[216:217], off sc0
	s_add_i32 m0, s20, 0x2000
	s_add_u32 s20, s24, 0x200000
	s_addc_u32 s21, s25, 0
	s_add_i32 s47, s42, s33
	global_load_lds_dwordx4 v[218:219], off sc0
	v_lshl_add_u64 v[184:185], s[20:21], 0, v[130:131]
	s_mov_b32 m0, s47
	v_lshl_add_u64 v[220:221], s[26:27], 0, v[128:129]
	global_load_lds_dwordx4 v[184:185], off sc0
	v_lshl_add_u64 v[184:185], s[20:21], 0, v[134:135]
	s_add_i32 m0, s47, 0x2000
	v_lshl_add_u64 v[222:223], s[26:27], 0, v[132:133]
	global_load_lds_dwordx4 v[184:185], off sc0
	s_mov_b32 m0, s17
	s_nop 0
	global_load_lds_dwordx4 v[220:221], off sc0
	s_mov_b32 m0, s34
	s_nop 0
	global_load_lds_dwordx4 v[222:223], off sc0
	ds_read_b128 v[184:187], v154 offset:16384
	ds_read_b128 v[188:191], v154 offset:17408
	ds_read_b128 v[192:195], v154 offset:18432
	ds_read_b128 v[196:199], v154 offset:19456
	ds_read_b128 v[200:203], v154 offset:20480
	ds_read_b128 v[204:207], v154 offset:21504
	ds_read_b128 v[208:211], v154 offset:22528
	ds_read_b128 v[212:215], v154 offset:23552
	s_waitcnt vmcnt(8)
	s_waitcnt lgkmcnt(0)
	s_barrier
	v_mfma_f32_16x16x32_bf16 v[60:63], v[146:149], v[184:187], v[60:63]
	v_mfma_f32_16x16x32_bf16 v[60:63], v[156:159], v[188:191], v[60:63]
	v_mfma_f32_16x16x32_bf16 v[56:59], v[164:167], v[188:191], v[56:59]
	v_mfma_f32_16x16x32_bf16 v[56:59], v[160:163], v[184:187], v[56:59]
	v_mfma_f32_16x16x32_bf16 v[52:55], v[168:171], v[184:187], v[52:55]
	v_mfma_f32_16x16x32_bf16 v[52:55], v[172:175], v[188:191], v[52:55]
	v_mfma_f32_16x16x32_bf16 v[44:47], v[180:183], v[188:191], v[44:47]
	v_mfma_f32_16x16x32_bf16 v[44:47], v[176:179], v[184:187], v[44:47]
	v_mfma_f32_16x16x32_bf16 v[28:31], v[176:179], v[192:195], v[28:31]
	v_mfma_f32_16x16x32_bf16 v[28:31], v[180:183], v[196:199], v[28:31]
	v_mfma_f32_16x16x32_bf16 v[36:39], v[172:175], v[196:199], v[36:39]
	v_mfma_f32_16x16x32_bf16 v[36:39], v[168:171], v[192:195], v[36:39]
	v_mfma_f32_16x16x32_bf16 v[40:43], v[160:163], v[192:195], v[40:43]
	v_mfma_f32_16x16x32_bf16 v[40:43], v[164:167], v[196:199], v[40:43]
	v_mfma_f32_16x16x32_bf16 v[48:51], v[156:159], v[196:199], v[48:51]
	v_mfma_f32_16x16x32_bf16 v[48:51], v[146:149], v[192:195], v[48:51]
	v_mfma_f32_16x16x32_bf16 v[32:35], v[146:149], v[200:203], v[32:35]
	v_mfma_f32_16x16x32_bf16 v[32:35], v[156:159], v[204:207], v[32:35]
	v_mfma_f32_16x16x32_bf16 v[24:27], v[164:167], v[204:207], v[24:27]
	v_mfma_f32_16x16x32_bf16 v[24:27], v[160:163], v[200:203], v[24:27]
	v_mfma_f32_16x16x32_bf16 v[20:23], v[168:171], v[200:203], v[20:23]
	v_mfma_f32_16x16x32_bf16 v[20:23], v[172:175], v[204:207], v[20:23]
	v_mfma_f32_16x16x32_bf16 v[12:15], v[180:183], v[204:207], v[12:15]
	v_mfma_f32_16x16x32_bf16 v[12:15], v[176:179], v[200:203], v[12:15]
	v_mfma_f32_16x16x32_bf16 v[0:3], v[176:179], v[208:211], v[0:3]
	v_mfma_f32_16x16x32_bf16 v[0:3], v[180:183], v[212:215], v[0:3]
	v_mfma_f32_16x16x32_bf16 v[4:7], v[172:175], v[212:215], v[4:7]
	v_mfma_f32_16x16x32_bf16 v[4:7], v[168:171], v[208:211], v[4:7]
	v_mfma_f32_16x16x32_bf16 v[8:11], v[160:163], v[208:211], v[8:11]
	v_mfma_f32_16x16x32_bf16 v[8:11], v[164:167], v[212:215], v[8:11]
	v_mfma_f32_16x16x32_bf16 v[16:19], v[156:159], v[212:215], v[16:19]
	v_mfma_f32_16x16x32_bf16 v[16:19], v[146:149], v[208:211], v[16:19]
	s_barrier
	s_add_i32 s47, 0, 0x18000
	v_add_u32_e32 v144, s47, v145
	s_add_i32 s48, 0, 0x1c000
	ds_read_b128 v[146:149], v144
	ds_read_b128 v[156:159], v144 offset:1024
	ds_read_b128 v[160:163], v144 offset:2048
	ds_read_b128 v[164:167], v144 offset:3072
	v_add_u32_e32 v144, s48, v145
	ds_read_b128 v[168:171], v144
	ds_read_b128 v[172:175], v144 offset:1024
	ds_read_b128 v[176:179], v144 offset:2048
	ds_read_b128 v[180:183], v144 offset:3072
	s_add_u32 s20, s26, 0x200000
	s_addc_u32 s21, s27, 0
	s_mov_b32 m0, s35
	v_lshl_add_u64 v[184:185], s[20:21], 0, v[128:129]
	global_load_lds_dwordx4 v[184:185], off sc0
	v_lshl_add_u64 v[184:185], s[20:21], 0, v[132:133]
	s_mov_b32 m0, s36
	s_nop 0
	global_load_lds_dwordx4 v[184:185], off sc0
	ds_read_b128 v[184:187], v154 offset:32768
	ds_read_b128 v[188:191], v154 offset:33792
	ds_read_b128 v[192:195], v154 offset:34816
	ds_read_b128 v[196:199], v154 offset:35840
	ds_read_b128 v[200:203], v154 offset:36864
	ds_read_b128 v[204:207], v154 offset:37888
	ds_read_b128 v[208:211], v154 offset:38912
	ds_read_b128 v[212:215], v154 offset:39936
	s_waitcnt vmcnt(8)
	s_waitcnt lgkmcnt(0)
	s_barrier
	v_mfma_f32_16x16x32_bf16 v[124:127], v[146:149], v[184:187], v[124:127]
	v_mfma_f32_16x16x32_bf16 v[124:127], v[156:159], v[188:191], v[124:127]
	v_mfma_f32_16x16x32_bf16 v[120:123], v[164:167], v[188:191], v[120:123]
	v_mfma_f32_16x16x32_bf16 v[120:123], v[160:163], v[184:187], v[120:123]
	v_mfma_f32_16x16x32_bf16 v[116:119], v[168:171], v[184:187], v[116:119]
	v_mfma_f32_16x16x32_bf16 v[116:119], v[172:175], v[188:191], v[116:119]
	v_mfma_f32_16x16x32_bf16 v[108:111], v[180:183], v[188:191], v[108:111]
	v_mfma_f32_16x16x32_bf16 v[108:111], v[176:179], v[184:187], v[108:111]
	v_mfma_f32_16x16x32_bf16 v[92:95], v[176:179], v[192:195], v[92:95]
	v_mfma_f32_16x16x32_bf16 v[92:95], v[180:183], v[196:199], v[92:95]
	v_mfma_f32_16x16x32_bf16 v[100:103], v[172:175], v[196:199], v[100:103]
	v_mfma_f32_16x16x32_bf16 v[100:103], v[168:171], v[192:195], v[100:103]
	v_mfma_f32_16x16x32_bf16 v[104:107], v[160:163], v[192:195], v[104:107]
	v_mfma_f32_16x16x32_bf16 v[104:107], v[164:167], v[196:199], v[104:107]
	v_mfma_f32_16x16x32_bf16 v[112:115], v[156:159], v[196:199], v[112:115]
	v_mfma_f32_16x16x32_bf16 v[112:115], v[146:149], v[192:195], v[112:115]
	v_mfma_f32_16x16x32_bf16 v[96:99], v[146:149], v[200:203], v[96:99]
	v_mfma_f32_16x16x32_bf16 v[96:99], v[156:159], v[204:207], v[96:99]
	v_mfma_f32_16x16x32_bf16 v[88:91], v[164:167], v[204:207], v[88:91]
	v_mfma_f32_16x16x32_bf16 v[88:91], v[160:163], v[200:203], v[88:91]
	v_mfma_f32_16x16x32_bf16 v[84:87], v[168:171], v[200:203], v[84:87]
	v_mfma_f32_16x16x32_bf16 v[84:87], v[172:175], v[204:207], v[84:87]
	v_mfma_f32_16x16x32_bf16 v[76:79], v[180:183], v[204:207], v[76:79]
	v_mfma_f32_16x16x32_bf16 v[76:79], v[176:179], v[200:203], v[76:79]
	v_mfma_f32_16x16x32_bf16 v[64:67], v[176:179], v[208:211], v[64:67]
	v_mfma_f32_16x16x32_bf16 v[64:67], v[180:183], v[212:215], v[64:67]
	v_mfma_f32_16x16x32_bf16 v[68:71], v[172:175], v[212:215], v[68:71]
	v_mfma_f32_16x16x32_bf16 v[68:71], v[168:171], v[208:211], v[68:71]
	v_mfma_f32_16x16x32_bf16 v[72:75], v[160:163], v[208:211], v[72:75]
	v_mfma_f32_16x16x32_bf16 v[72:75], v[164:167], v[212:215], v[72:75]
	v_mfma_f32_16x16x32_bf16 v[80:83], v[156:159], v[212:215], v[80:83]
	v_mfma_f32_16x16x32_bf16 v[80:83], v[146:149], v[208:211], v[80:83]
	s_barrier
	s_add_i32 s20, s47, s33
	v_lshl_add_u64 v[184:185], v[216:217], 0, s[12:13]
	s_mov_b32 m0, s20
	s_nop 0
	global_load_lds_dwordx4 v[184:185], off sc0
	s_add_i32 m0, s20, 0x2000
	s_add_u32 s20, s24, 0x200080
	v_lshl_add_u64 v[184:185], v[218:219], 0, s[12:13]
	s_addc_u32 s21, s25, 0
	s_add_i32 s24, s48, s33
	global_load_lds_dwordx4 v[184:185], off sc0
	v_lshl_add_u64 v[184:185], s[20:21], 0, v[130:131]
	s_mov_b32 m0, s24
	s_nop 0
	global_load_lds_dwordx4 v[184:185], off sc0
	v_lshl_add_u64 v[184:185], s[20:21], 0, v[134:135]
	s_add_i32 m0, s24, 0x2000
	s_nop 0
	global_load_lds_dwordx4 v[184:185], off sc0
	v_lshl_add_u64 v[184:185], v[220:221], 0, s[12:13]
	s_mov_b32 m0, s37
	s_nop 0
	global_load_lds_dwordx4 v[184:185], off sc0
	v_lshl_add_u64 v[184:185], v[222:223], 0, s[12:13]
	s_mov_b32 m0, s38
	s_nop 0
	global_load_lds_dwordx4 v[184:185], off sc0
	ds_read_b128 v[184:187], v154 offset:49152
	ds_read_b128 v[188:191], v154 offset:50176
	ds_read_b128 v[192:195], v154 offset:51200
	ds_read_b128 v[196:199], v154 offset:52224
	ds_read_b128 v[200:203], v154 offset:53248
	ds_read_b128 v[204:207], v154 offset:54272
	ds_read_b128 v[208:211], v154 offset:55296
	ds_read_b128 v[212:215], v154 offset:56320
	s_waitcnt vmcnt(8)
	s_waitcnt lgkmcnt(0)
	s_barrier
	v_mfma_f32_16x16x32_bf16 v[60:63], v[146:149], v[184:187], v[60:63]
	v_mfma_f32_16x16x32_bf16 v[60:63], v[156:159], v[188:191], v[60:63]
	v_mfma_f32_16x16x32_bf16 v[56:59], v[164:167], v[188:191], v[56:59]
	v_mfma_f32_16x16x32_bf16 v[56:59], v[160:163], v[184:187], v[56:59]
	v_mfma_f32_16x16x32_bf16 v[52:55], v[168:171], v[184:187], v[52:55]
	v_mfma_f32_16x16x32_bf16 v[52:55], v[172:175], v[188:191], v[52:55]
	v_mfma_f32_16x16x32_bf16 v[44:47], v[180:183], v[188:191], v[44:47]
	v_mfma_f32_16x16x32_bf16 v[44:47], v[176:179], v[184:187], v[44:47]
	v_mfma_f32_16x16x32_bf16 v[28:31], v[176:179], v[192:195], v[28:31]
	v_mfma_f32_16x16x32_bf16 v[28:31], v[180:183], v[196:199], v[28:31]
	v_mfma_f32_16x16x32_bf16 v[36:39], v[172:175], v[196:199], v[36:39]
	v_mfma_f32_16x16x32_bf16 v[36:39], v[168:171], v[192:195], v[36:39]
	v_mfma_f32_16x16x32_bf16 v[40:43], v[160:163], v[192:195], v[40:43]
	v_mfma_f32_16x16x32_bf16 v[40:43], v[164:167], v[196:199], v[40:43]
	v_mfma_f32_16x16x32_bf16 v[48:51], v[156:159], v[196:199], v[48:51]
	v_mfma_f32_16x16x32_bf16 v[48:51], v[146:149], v[192:195], v[48:51]
	v_mfma_f32_16x16x32_bf16 v[32:35], v[146:149], v[200:203], v[32:35]
	v_mfma_f32_16x16x32_bf16 v[32:35], v[156:159], v[204:207], v[32:35]
	v_mfma_f32_16x16x32_bf16 v[24:27], v[164:167], v[204:207], v[24:27]
	v_mfma_f32_16x16x32_bf16 v[24:27], v[160:163], v[200:203], v[24:27]
	v_mfma_f32_16x16x32_bf16 v[20:23], v[168:171], v[200:203], v[20:23]
	v_mfma_f32_16x16x32_bf16 v[20:23], v[172:175], v[204:207], v[20:23]
	v_mfma_f32_16x16x32_bf16 v[12:15], v[180:183], v[204:207], v[12:15]
	v_mfma_f32_16x16x32_bf16 v[12:15], v[176:179], v[200:203], v[12:15]
	v_mfma_f32_16x16x32_bf16 v[0:3], v[176:179], v[208:211], v[0:3]
	v_mfma_f32_16x16x32_bf16 v[0:3], v[180:183], v[212:215], v[0:3]
	v_mfma_f32_16x16x32_bf16 v[4:7], v[172:175], v[212:215], v[4:7]
	v_mfma_f32_16x16x32_bf16 v[4:7], v[168:171], v[208:211], v[4:7]
	v_mfma_f32_16x16x32_bf16 v[8:11], v[160:163], v[208:211], v[8:11]
	v_mfma_f32_16x16x32_bf16 v[8:11], v[164:167], v[212:215], v[8:11]
	v_mfma_f32_16x16x32_bf16 v[16:19], v[156:159], v[212:215], v[16:19]
	v_mfma_f32_16x16x32_bf16 v[16:19], v[146:149], v[208:211], v[16:19]
	s_barrier
	s_add_i32 s46, s46, 2
	s_add_u32 s6, s6, 0x100
	s_addc_u32 s15, s15, 0
	s_cmp_gt_u32 s46, 13
	s_mov_b64 s[20:21], s[22:23]
	s_cbranch_scc0 .LBB0_1263
	s_and_b64 vcc, exec, s[8:9]
	s_cbranch_vccz .LBB0_1266
	s_barrier

.LBB0_1340:
	v_add_u32_e32 v166, s51, v152
	v_add_u32_e32 v182, s52, v152
	ds_read_b128 v[154:157], v166
	ds_read_b128 v[158:161], v166 offset:1024
	ds_read_b128 v[162:165], v166 offset:2048
	ds_read_b128 v[166:169], v166 offset:3072
	ds_read_b128 v[170:173], v182
	ds_read_b128 v[174:177], v182 offset:1024
	ds_read_b128 v[178:181], v182 offset:2048
	ds_read_b128 v[182:185], v182 offset:3072
	s_add_u32 s30, s10, s28
	s_addc_u32 s31, s11, s29
	s_cmp_eq_u32 s58, 60
	s_cselect_b32 s35, s23, s31
	s_cselect_b32 s34, s54, s30
	s_cselect_b32 s31, s21, s57
	s_cselect_b32 s30, s55, s56
	v_lshl_add_u64 v[186:187], s[10:11], 0, v[146:147]
	s_add_i32 m0, s44, 0xc000
	s_nop 0
	global_load_lds_dwordx4 v[186:187], off sc0
	v_lshl_add_u64 v[186:187], s[10:11], 0, v[144:145]
	s_add_i32 m0, s44, 0xe000
	s_nop 0
	global_load_lds_dwordx4 v[186:187], off sc0
	ds_read_b128 v[186:189], v153
	ds_read_b128 v[190:193], v153 offset:1024
	ds_read_b128 v[194:197], v153 offset:2048
	ds_read_b128 v[198:201], v153 offset:3072
	ds_read_b128 v[202:205], v153 offset:4096
	ds_read_b128 v[206:209], v153 offset:5120
	ds_read_b128 v[210:213], v153 offset:6144
	ds_read_b128 v[214:217], v153 offset:7168
	s_waitcnt vmcnt(8)
	s_waitcnt lgkmcnt(0)
	s_barrier
	v_mfma_f32_16x16x32_bf16 v[124:127], v[154:157], v[186:189], v[124:127]
	v_mfma_f32_16x16x32_bf16 v[124:127], v[158:161], v[190:193], v[124:127]
	v_mfma_f32_16x16x32_bf16 v[120:123], v[166:169], v[190:193], v[120:123]
	v_mfma_f32_16x16x32_bf16 v[120:123], v[162:165], v[186:189], v[120:123]
	v_mfma_f32_16x16x32_bf16 v[116:119], v[170:173], v[186:189], v[116:119]
	v_mfma_f32_16x16x32_bf16 v[116:119], v[174:177], v[190:193], v[116:119]
	v_mfma_f32_16x16x32_bf16 v[112:115], v[182:185], v[190:193], v[112:115]
	v_mfma_f32_16x16x32_bf16 v[112:115], v[178:181], v[186:189], v[112:115]
	v_mfma_f32_16x16x32_bf16 v[96:99], v[178:181], v[194:197], v[96:99]
	v_mfma_f32_16x16x32_bf16 v[96:99], v[182:185], v[198:201], v[96:99]
	v_mfma_f32_16x16x32_bf16 v[100:103], v[174:177], v[198:201], v[100:103]
	v_mfma_f32_16x16x32_bf16 v[100:103], v[170:173], v[194:197], v[100:103]
	v_mfma_f32_16x16x32_bf16 v[104:107], v[162:165], v[194:197], v[104:107]
	v_mfma_f32_16x16x32_bf16 v[104:107], v[166:169], v[198:201], v[104:107]
	v_mfma_f32_16x16x32_bf16 v[108:111], v[158:161], v[198:201], v[108:111]
	v_mfma_f32_16x16x32_bf16 v[108:111], v[154:157], v[194:197], v[108:111]
	v_mfma_f32_16x16x32_bf16 v[92:95], v[154:157], v[202:205], v[92:95]
	v_mfma_f32_16x16x32_bf16 v[92:95], v[158:161], v[206:209], v[92:95]
	v_mfma_f32_16x16x32_bf16 v[88:91], v[166:169], v[206:209], v[88:91]
	v_mfma_f32_16x16x32_bf16 v[88:91], v[162:165], v[202:205], v[88:91]
	v_mfma_f32_16x16x32_bf16 v[84:87], v[170:173], v[202:205], v[84:87]
	v_mfma_f32_16x16x32_bf16 v[84:87], v[174:177], v[206:209], v[84:87]
	v_mfma_f32_16x16x32_bf16 v[80:83], v[182:185], v[206:209], v[80:83]
	v_mfma_f32_16x16x32_bf16 v[80:83], v[178:181], v[202:205], v[80:83]
	v_mfma_f32_16x16x32_bf16 v[64:67], v[178:181], v[210:213], v[64:67]
	v_mfma_f32_16x16x32_bf16 v[64:67], v[182:185], v[214:217], v[64:67]
	v_mfma_f32_16x16x32_bf16 v[68:71], v[174:177], v[214:217], v[68:71]
	v_mfma_f32_16x16x32_bf16 v[68:71], v[170:173], v[210:213], v[68:71]
	v_mfma_f32_16x16x32_bf16 v[72:75], v[162:165], v[210:213], v[72:75]
	v_mfma_f32_16x16x32_bf16 v[72:75], v[166:169], v[214:217], v[72:75]
	v_mfma_f32_16x16x32_bf16 v[76:79], v[158:161], v[214:217], v[76:79]
	v_mfma_f32_16x16x32_bf16 v[76:79], v[154:157], v[210:213], v[76:79]
	s_barrier
	s_add_i32 s59, s51, s43
	v_lshl_add_u64 v[218:219], s[30:31], 0, v[130:131]
	s_mov_b32 m0, s59
	v_lshl_add_u64 v[220:221], s[30:31], 0, v[134:135]
	global_load_lds_dwordx4 v[218:219], off sc0
	s_add_i32 m0, s59, 0x2000
	s_add_u32 s60, s30, 0x100000
	s_addc_u32 s61, s31, 0
	s_add_i32 s59, s52, s43
	global_load_lds_dwordx4 v[220:221], off sc0
	v_lshl_add_u64 v[186:187], s[60:61], 0, v[130:131]
	s_mov_b32 m0, s59
	v_lshl_add_u64 v[222:223], s[34:35], 0, v[128:129]
	global_load_lds_dwordx4 v[186:187], off sc0
	v_lshl_add_u64 v[186:187], s[60:61], 0, v[134:135]
	s_add_i32 m0, s59, 0x2000
	v_lshl_add_u64 v[224:225], s[34:35], 0, v[132:133]
	global_load_lds_dwordx4 v[186:187], off sc0
	s_mov_b32 m0, s44
	s_nop 0
	global_load_lds_dwordx4 v[222:223], off sc0
	s_mov_b32 m0, s45
	s_nop 0
	global_load_lds_dwordx4 v[224:225], off sc0
	ds_read_b128 v[186:189], v153 offset:16384
	ds_read_b128 v[190:193], v153 offset:17408
	ds_read_b128 v[194:197], v153 offset:18432
	ds_read_b128 v[198:201], v153 offset:19456
	ds_read_b128 v[202:205], v153 offset:20480
	ds_read_b128 v[206:209], v153 offset:21504
	ds_read_b128 v[210:213], v153 offset:22528
	ds_read_b128 v[214:217], v153 offset:23552
	s_waitcnt vmcnt(8)
	s_waitcnt lgkmcnt(0)
	s_barrier
	v_mfma_f32_16x16x32_bf16 v[60:63], v[154:157], v[186:189], v[60:63]
	v_mfma_f32_16x16x32_bf16 v[60:63], v[158:161], v[190:193], v[60:63]
	v_mfma_f32_16x16x32_bf16 v[56:59], v[166:169], v[190:193], v[56:59]
	v_mfma_f32_16x16x32_bf16 v[56:59], v[162:165], v[186:189], v[56:59]
	v_mfma_f32_16x16x32_bf16 v[52:55], v[170:173], v[186:189], v[52:55]
	v_mfma_f32_16x16x32_bf16 v[52:55], v[174:177], v[190:193], v[52:55]
	v_mfma_f32_16x16x32_bf16 v[48:51], v[182:185], v[190:193], v[48:51]
	v_mfma_f32_16x16x32_bf16 v[48:51], v[178:181], v[186:189], v[48:51]
	v_mfma_f32_16x16x32_bf16 v[32:35], v[178:181], v[194:197], v[32:35]
	v_mfma_f32_16x16x32_bf16 v[32:35], v[182:185], v[198:201], v[32:35]
	v_mfma_f32_16x16x32_bf16 v[36:39], v[174:177], v[198:201], v[36:39]
	v_mfma_f32_16x16x32_bf16 v[36:39], v[170:173], v[194:197], v[36:39]
	v_mfma_f32_16x16x32_bf16 v[40:43], v[162:165], v[194:197], v[40:43]
	v_mfma_f32_16x16x32_bf16 v[40:43], v[166:169], v[198:201], v[40:43]
	v_mfma_f32_16x16x32_bf16 v[44:47], v[158:161], v[198:201], v[44:47]
	v_mfma_f32_16x16x32_bf16 v[44:47], v[154:157], v[194:197], v[44:47]
	v_mfma_f32_16x16x32_bf16 v[28:31], v[154:157], v[202:205], v[28:31]
	v_mfma_f32_16x16x32_bf16 v[28:31], v[158:161], v[206:209], v[28:31]
	v_mfma_f32_16x16x32_bf16 v[24:27], v[166:169], v[206:209], v[24:27]
	v_mfma_f32_16x16x32_bf16 v[24:27], v[162:165], v[202:205], v[24:27]
	v_mfma_f32_16x16x32_bf16 v[20:23], v[170:173], v[202:205], v[20:23]
	v_mfma_f32_16x16x32_bf16 v[20:23], v[174:177], v[206:209], v[20:23]
	v_mfma_f32_16x16x32_bf16 v[16:19], v[182:185], v[206:209], v[16:19]
	v_mfma_f32_16x16x32_bf16 v[16:19], v[178:181], v[202:205], v[16:19]
	v_mfma_f32_16x16x32_bf16 v[0:3], v[178:181], v[210:213], v[0:3]
	v_mfma_f32_16x16x32_bf16 v[0:3], v[182:185], v[214:217], v[0:3]
	v_mfma_f32_16x16x32_bf16 v[4:7], v[174:177], v[214:217], v[4:7]
	v_mfma_f32_16x16x32_bf16 v[4:7], v[170:173], v[210:213], v[4:7]
	v_mfma_f32_16x16x32_bf16 v[8:11], v[162:165], v[210:213], v[8:11]
	v_mfma_f32_16x16x32_bf16 v[8:11], v[166:169], v[214:217], v[8:11]
	v_mfma_f32_16x16x32_bf16 v[12:15], v[158:161], v[214:217], v[12:15]
	v_mfma_f32_16x16x32_bf16 v[12:15], v[154:157], v[210:213], v[12:15]
	s_barrier
	s_add_i32 s59, 0, 0x18000
	s_add_i32 s60, 0, 0x1c000
	v_add_u32_e32 v166, s59, v152
	v_add_u32_e32 v182, s60, v152
	ds_read_b128 v[154:157], v166
	ds_read_b128 v[158:161], v166 offset:1024
	ds_read_b128 v[162:165], v166 offset:2048
	ds_read_b128 v[166:169], v166 offset:3072
	ds_read_b128 v[170:173], v182
	ds_read_b128 v[174:177], v182 offset:1024
	ds_read_b128 v[178:181], v182 offset:2048
	ds_read_b128 v[182:185], v182 offset:3072
	s_add_u32 s34, s34, 0x100000
	s_addc_u32 s35, s35, 0
	s_mov_b32 m0, s46
	v_lshl_add_u64 v[186:187], s[34:35], 0, v[128:129]
	global_load_lds_dwordx4 v[186:187], off sc0
	v_lshl_add_u64 v[186:187], s[34:35], 0, v[132:133]
	s_mov_b32 m0, s47
	s_nop 0
	global_load_lds_dwordx4 v[186:187], off sc0
	ds_read_b128 v[186:189], v153 offset:32768
	ds_read_b128 v[190:193], v153 offset:33792
	ds_read_b128 v[194:197], v153 offset:34816
	ds_read_b128 v[198:201], v153 offset:35840
	ds_read_b128 v[202:205], v153 offset:36864
	ds_read_b128 v[206:209], v153 offset:37888
	ds_read_b128 v[210:213], v153 offset:38912
	ds_read_b128 v[214:217], v153 offset:39936
	s_waitcnt vmcnt(8)
	s_waitcnt lgkmcnt(0)
	s_barrier
	v_mfma_f32_16x16x32_bf16 v[124:127], v[154:157], v[186:189], v[124:127]
	v_mfma_f32_16x16x32_bf16 v[124:127], v[158:161], v[190:193], v[124:127]
	v_mfma_f32_16x16x32_bf16 v[120:123], v[166:169], v[190:193], v[120:123]
	v_mfma_f32_16x16x32_bf16 v[120:123], v[162:165], v[186:189], v[120:123]
	v_mfma_f32_16x16x32_bf16 v[116:119], v[170:173], v[186:189], v[116:119]
	v_mfma_f32_16x16x32_bf16 v[116:119], v[174:177], v[190:193], v[116:119]
	v_mfma_f32_16x16x32_bf16 v[112:115], v[182:185], v[190:193], v[112:115]
	v_mfma_f32_16x16x32_bf16 v[112:115], v[178:181], v[186:189], v[112:115]
	v_mfma_f32_16x16x32_bf16 v[96:99], v[178:181], v[194:197], v[96:99]
	v_mfma_f32_16x16x32_bf16 v[96:99], v[182:185], v[198:201], v[96:99]
	v_mfma_f32_16x16x32_bf16 v[100:103], v[174:177], v[198:201], v[100:103]
	v_mfma_f32_16x16x32_bf16 v[100:103], v[170:173], v[194:197], v[100:103]
	v_mfma_f32_16x16x32_bf16 v[104:107], v[162:165], v[194:197], v[104:107]
	v_mfma_f32_16x16x32_bf16 v[104:107], v[166:169], v[198:201], v[104:107]
	v_mfma_f32_16x16x32_bf16 v[108:111], v[158:161], v[198:201], v[108:111]
	v_mfma_f32_16x16x32_bf16 v[108:111], v[154:157], v[194:197], v[108:111]
	v_mfma_f32_16x16x32_bf16 v[92:95], v[154:157], v[202:205], v[92:95]
	v_mfma_f32_16x16x32_bf16 v[92:95], v[158:161], v[206:209], v[92:95]
	v_mfma_f32_16x16x32_bf16 v[88:91], v[166:169], v[206:209], v[88:91]
	v_mfma_f32_16x16x32_bf16 v[88:91], v[162:165], v[202:205], v[88:91]
	v_mfma_f32_16x16x32_bf16 v[84:87], v[170:173], v[202:205], v[84:87]
	v_mfma_f32_16x16x32_bf16 v[84:87], v[174:177], v[206:209], v[84:87]
	v_mfma_f32_16x16x32_bf16 v[80:83], v[182:185], v[206:209], v[80:83]
	v_mfma_f32_16x16x32_bf16 v[80:83], v[178:181], v[202:205], v[80:83]
	v_mfma_f32_16x16x32_bf16 v[64:67], v[178:181], v[210:213], v[64:67]
	v_mfma_f32_16x16x32_bf16 v[64:67], v[182:185], v[214:217], v[64:67]
	v_mfma_f32_16x16x32_bf16 v[68:71], v[174:177], v[214:217], v[68:71]
	v_mfma_f32_16x16x32_bf16 v[68:71], v[170:173], v[210:213], v[68:71]
	v_mfma_f32_16x16x32_bf16 v[72:75], v[162:165], v[210:213], v[72:75]
	v_mfma_f32_16x16x32_bf16 v[72:75], v[166:169], v[214:217], v[72:75]
	v_mfma_f32_16x16x32_bf16 v[76:79], v[158:161], v[214:217], v[76:79]
	v_mfma_f32_16x16x32_bf16 v[76:79], v[154:157], v[210:213], v[76:79]
	s_barrier
	s_add_i32 s34, s59, s43
	v_lshl_add_u64 v[186:187], v[218:219], 0, s[14:15]
	s_mov_b32 m0, s34
	s_nop 0
	global_load_lds_dwordx4 v[186:187], off sc0
	s_add_i32 m0, s34, 0x2000
	s_add_u32 s30, s30, 0x100080
	v_lshl_add_u64 v[186:187], v[220:221], 0, s[14:15]
	s_addc_u32 s31, s31, 0
	s_add_i32 s34, s60, s43
	global_load_lds_dwordx4 v[186:187], off sc0
	v_lshl_add_u64 v[186:187], s[30:31], 0, v[130:131]
	s_mov_b32 m0, s34
	s_nop 0
	global_load_lds_dwordx4 v[186:187], off sc0
	v_lshl_add_u64 v[186:187], s[30:31], 0, v[134:135]
	s_add_i32 m0, s34, 0x2000
	s_nop 0
	global_load_lds_dwordx4 v[186:187], off sc0
	v_lshl_add_u64 v[186:187], v[222:223], 0, s[16:17]
	s_mov_b32 m0, s49
	s_nop 0
	global_load_lds_dwordx4 v[186:187], off sc0
	v_lshl_add_u64 v[186:187], v[224:225], 0, s[16:17]
	s_mov_b32 m0, s50
	s_nop 0
	global_load_lds_dwordx4 v[186:187], off sc0
	ds_read_b128 v[186:189], v153 offset:49152
	ds_read_b128 v[190:193], v153 offset:50176
	ds_read_b128 v[194:197], v153 offset:51200
	ds_read_b128 v[198:201], v153 offset:52224
	ds_read_b128 v[202:205], v153 offset:53248
	ds_read_b128 v[206:209], v153 offset:54272
	ds_read_b128 v[210:213], v153 offset:55296
	ds_read_b128 v[214:217], v153 offset:56320
	s_waitcnt vmcnt(8)
	s_waitcnt lgkmcnt(0)
	s_barrier
	v_mfma_f32_16x16x32_bf16 v[60:63], v[154:157], v[186:189], v[60:63]
	v_mfma_f32_16x16x32_bf16 v[60:63], v[158:161], v[190:193], v[60:63]
	v_mfma_f32_16x16x32_bf16 v[56:59], v[166:169], v[190:193], v[56:59]
	v_mfma_f32_16x16x32_bf16 v[56:59], v[162:165], v[186:189], v[56:59]
	v_mfma_f32_16x16x32_bf16 v[52:55], v[170:173], v[186:189], v[52:55]
	v_mfma_f32_16x16x32_bf16 v[52:55], v[174:177], v[190:193], v[52:55]
	v_mfma_f32_16x16x32_bf16 v[48:51], v[182:185], v[190:193], v[48:51]
	v_mfma_f32_16x16x32_bf16 v[48:51], v[178:181], v[186:189], v[48:51]
	v_mfma_f32_16x16x32_bf16 v[32:35], v[178:181], v[194:197], v[32:35]
	v_mfma_f32_16x16x32_bf16 v[32:35], v[182:185], v[198:201], v[32:35]
	v_mfma_f32_16x16x32_bf16 v[36:39], v[174:177], v[198:201], v[36:39]
	v_mfma_f32_16x16x32_bf16 v[36:39], v[170:173], v[194:197], v[36:39]
	v_mfma_f32_16x16x32_bf16 v[40:43], v[162:165], v[194:197], v[40:43]
	v_mfma_f32_16x16x32_bf16 v[40:43], v[166:169], v[198:201], v[40:43]
	v_mfma_f32_16x16x32_bf16 v[44:47], v[158:161], v[198:201], v[44:47]
	v_mfma_f32_16x16x32_bf16 v[44:47], v[154:157], v[194:197], v[44:47]
	v_mfma_f32_16x16x32_bf16 v[28:31], v[154:157], v[202:205], v[28:31]
	v_mfma_f32_16x16x32_bf16 v[28:31], v[158:161], v[206:209], v[28:31]
	v_mfma_f32_16x16x32_bf16 v[24:27], v[166:169], v[206:209], v[24:27]
	v_mfma_f32_16x16x32_bf16 v[24:27], v[162:165], v[202:205], v[24:27]
	v_mfma_f32_16x16x32_bf16 v[20:23], v[170:173], v[202:205], v[20:23]
	v_mfma_f32_16x16x32_bf16 v[20:23], v[174:177], v[206:209], v[20:23]
	v_mfma_f32_16x16x32_bf16 v[16:19], v[182:185], v[206:209], v[16:19]
	v_mfma_f32_16x16x32_bf16 v[16:19], v[178:181], v[202:205], v[16:19]
	v_mfma_f32_16x16x32_bf16 v[0:3], v[178:181], v[210:213], v[0:3]
	v_mfma_f32_16x16x32_bf16 v[0:3], v[182:185], v[214:217], v[0:3]
	v_mfma_f32_16x16x32_bf16 v[4:7], v[174:177], v[214:217], v[4:7]
	v_mfma_f32_16x16x32_bf16 v[4:7], v[170:173], v[210:213], v[4:7]
	v_mfma_f32_16x16x32_bf16 v[8:11], v[162:165], v[210:213], v[8:11]
	v_mfma_f32_16x16x32_bf16 v[8:11], v[166:169], v[214:217], v[8:11]
	v_mfma_f32_16x16x32_bf16 v[12:15], v[158:161], v[214:217], v[12:15]
	v_mfma_f32_16x16x32_bf16 v[12:15], v[154:157], v[210:213], v[12:15]
	s_barrier
	s_add_i32 s58, s58, 2
	s_add_u32 s56, s56, 0x100
	s_addc_u32 s57, s57, 0
	s_add_u32 s28, s28, 0x1000
	s_addc_u32 s29, s29, 0
	v_lshl_add_u64 v[146:147], v[146:147], 0, s[18:19]
	s_cmp_gt_u32 s58, 61
	v_lshl_add_u64 v[144:145], v[144:145], 0, s[18:19]
	s_cbranch_scc0 .LBB0_1340
	s_andn2_b64 vcc, exec, s[4:5]
	s_cbranch_vccnz .LBB0_1332
	v_mov_b32_e32 v0, 0
	s_mov_b32 s7, s20
	s_mov_b32 s6, s22
	s_mov_b64 s[8:9], s[26:27]
	s_mov_b64 s[10:11], s[24:25]
	s_mov_b32 s48, s53
	v_mov_b32_e32 v1, v0
	v_mov_b32_e32 v2, v0
	v_mov_b32_e32 v3, v0
	v_mov_b32_e32 v4, v0
	v_mov_b32_e32 v5, v0
	v_mov_b32_e32 v6, v0
	v_mov_b32_e32 v7, v0
	v_mov_b32_e32 v16, v0
	v_mov_b32_e32 v17, v0
	v_mov_b32_e32 v18, v0
	v_mov_b32_e32 v19, v0
	v_mov_b32_e32 v20, v0
	v_mov_b32_e32 v21, v0
	v_mov_b32_e32 v22, v0
	v_mov_b32_e32 v23, v0
	v_mov_b32_e32 v32, v0
	v_mov_b32_e32 v33, v0
	v_mov_b32_e32 v34, v0
	v_mov_b32_e32 v35, v0
	v_mov_b32_e32 v36, v0
	v_mov_b32_e32 v37, v0
	v_mov_b32_e32 v38, v0
	v_mov_b32_e32 v39, v0
	v_mov_b32_e32 v48, v0
	v_mov_b32_e32 v49, v0
	v_mov_b32_e32 v50, v0
	v_mov_b32_e32 v51, v0
	v_mov_b32_e32 v52, v0
	v_mov_b32_e32 v53, v0
	v_mov_b32_e32 v54, v0
	v_mov_b32_e32 v55, v0
	v_mov_b32_e32 v8, v0
	v_mov_b32_e32 v9, v0
	v_mov_b32_e32 v10, v0
	v_mov_b32_e32 v11, v0
	v_mov_b32_e32 v12, v0
	v_mov_b32_e32 v13, v0
	v_mov_b32_e32 v14, v0
	v_mov_b32_e32 v15, v0
	v_mov_b32_e32 v24, v0
	v_mov_b32_e32 v25, v0
	v_mov_b32_e32 v26, v0
	v_mov_b32_e32 v27, v0
	v_mov_b32_e32 v28, v0
	v_mov_b32_e32 v29, v0
	v_mov_b32_e32 v30, v0
	v_mov_b32_e32 v31, v0
	v_mov_b32_e32 v40, v0
	v_mov_b32_e32 v41, v0
	v_mov_b32_e32 v42, v0
	v_mov_b32_e32 v43, v0
	v_mov_b32_e32 v44, v0
	v_mov_b32_e32 v45, v0
	v_mov_b32_e32 v46, v0
	v_mov_b32_e32 v47, v0
	v_mov_b32_e32 v56, v0
	v_mov_b32_e32 v57, v0
	v_mov_b32_e32 v58, v0
	v_mov_b32_e32 v59, v0
	v_mov_b32_e32 v60, v0
	v_mov_b32_e32 v61, v0
	v_mov_b32_e32 v62, v0
	v_mov_b32_e32 v63, v0
	v_mov_b32_e32 v64, v0
	v_mov_b32_e32 v65, v0
	v_mov_b32_e32 v66, v0
	v_mov_b32_e32 v67, v0
	v_mov_b32_e32 v68, v0
	v_mov_b32_e32 v69, v0
	v_mov_b32_e32 v70, v0
	v_mov_b32_e32 v71, v0
	v_mov_b32_e32 v80, v0
	v_mov_b32_e32 v81, v0
	v_mov_b32_e32 v82, v0
	v_mov_b32_e32 v83, v0
	v_mov_b32_e32 v84, v0
	v_mov_b32_e32 v85, v0
	v_mov_b32_e32 v86, v0
	v_mov_b32_e32 v87, v0
	v_mov_b32_e32 v96, v0
	v_mov_b32_e32 v97, v0
	v_mov_b32_e32 v98, v0
	v_mov_b32_e32 v99, v0
	v_mov_b32_e32 v100, v0
	v_mov_b32_e32 v101, v0
	v_mov_b32_e32 v102, v0
	v_mov_b32_e32 v103, v0
	v_mov_b32_e32 v112, v0
	v_mov_b32_e32 v113, v0
	v_mov_b32_e32 v114, v0
	v_mov_b32_e32 v115, v0
	v_mov_b32_e32 v116, v0
	v_mov_b32_e32 v117, v0
	v_mov_b32_e32 v118, v0
	v_mov_b32_e32 v119, v0
	v_mov_b32_e32 v72, v0
	v_mov_b32_e32 v73, v0
	v_mov_b32_e32 v74, v0
	v_mov_b32_e32 v75, v0
	v_mov_b32_e32 v76, v0
	v_mov_b32_e32 v77, v0
	v_mov_b32_e32 v78, v0
	v_mov_b32_e32 v79, v0
	v_mov_b32_e32 v88, v0
	v_mov_b32_e32 v89, v0
	v_mov_b32_e32 v90, v0
	v_mov_b32_e32 v91, v0
	v_mov_b32_e32 v92, v0
	v_mov_b32_e32 v93, v0
	v_mov_b32_e32 v94, v0
	v_mov_b32_e32 v95, v0
	v_mov_b32_e32 v104, v0
	v_mov_b32_e32 v105, v0
	v_mov_b32_e32 v106, v0
	v_mov_b32_e32 v107, v0
	v_mov_b32_e32 v108, v0
	v_mov_b32_e32 v109, v0
	v_mov_b32_e32 v110, v0
	v_mov_b32_e32 v111, v0
	v_mov_b32_e32 v120, v0
	v_mov_b32_e32 v121, v0
	v_mov_b32_e32 v122, v0
	v_mov_b32_e32 v123, v0
	v_mov_b32_e32 v124, v0
	v_mov_b32_e32 v125, v0
	v_mov_b32_e32 v126, v0
	v_mov_b32_e32 v127, v0
	s_branch .LBB0_1332

.LBB0_1435:
	ds_read_b128 v[128:131], v180
	ds_read_b128 v[132:135], v180 offset:1024
	ds_read_b128 v[136:139], v180 offset:2048
	ds_read_b128 v[140:143], v180 offset:3072
	ds_read_b128 v[144:147], v181
	ds_read_b128 v[148:151], v181 offset:1024
	ds_read_b128 v[170:173], v181 offset:2048
	ds_read_b128 v[174:177], v181 offset:3072
	s_add_u32 s26, s24, 0xfffc0080
	s_addc_u32 s27, s25, -1
	s_cmp_eq_u32 s35, 12
	s_cselect_b32 s29, s1, s27
	s_cselect_b32 s28, s19, s26
	s_cselect_b32 s27, s17, s34
	s_cselect_b32 s26, s30, s31
	v_lshl_add_u64 v[184:185], s[24:25], 0, v[162:163]
	s_add_i32 m0, s40, 0xc000
	s_nop 0
	global_load_lds_dwordx4 v[184:185], off sc0
	v_lshl_add_u64 v[184:185], s[24:25], 0, v[164:165]
	s_add_i32 m0, s40, 0xe000
	s_nop 0
	global_load_lds_dwordx4 v[184:185], off sc0
	ds_read_b128 v[184:187], v182
	ds_read_b128 v[188:191], v182 offset:1024
	ds_read_b128 v[192:195], v182 offset:2048
	ds_read_b128 v[196:199], v182 offset:3072
	ds_read_b128 v[200:203], v182 offset:4096
	ds_read_b128 v[204:207], v182 offset:5120
	ds_read_b128 v[208:211], v182 offset:6144
	ds_read_b128 v[212:215], v182 offset:7168
	s_waitcnt vmcnt(8)
	s_waitcnt lgkmcnt(0)
	s_barrier
	v_mfma_f32_16x16x32_bf16 v[124:127], v[128:131], v[184:187], v[124:127]
	v_mfma_f32_16x16x32_bf16 v[124:127], v[132:135], v[188:191], v[124:127]
	v_mfma_f32_16x16x32_bf16 v[120:123], v[140:143], v[188:191], v[120:123]
	v_mfma_f32_16x16x32_bf16 v[120:123], v[136:139], v[184:187], v[120:123]
	v_mfma_f32_16x16x32_bf16 v[116:119], v[144:147], v[184:187], v[116:119]
	v_mfma_f32_16x16x32_bf16 v[116:119], v[148:151], v[188:191], v[116:119]
	v_mfma_f32_16x16x32_bf16 v[112:115], v[174:177], v[188:191], v[112:115]
	v_mfma_f32_16x16x32_bf16 v[112:115], v[170:173], v[184:187], v[112:115]
	v_mfma_f32_16x16x32_bf16 v[96:99], v[170:173], v[192:195], v[96:99]
	v_mfma_f32_16x16x32_bf16 v[96:99], v[174:177], v[196:199], v[96:99]
	v_mfma_f32_16x16x32_bf16 v[100:103], v[148:151], v[196:199], v[100:103]
	v_mfma_f32_16x16x32_bf16 v[100:103], v[144:147], v[192:195], v[100:103]
	v_mfma_f32_16x16x32_bf16 v[104:107], v[136:139], v[192:195], v[104:107]
	v_mfma_f32_16x16x32_bf16 v[104:107], v[140:143], v[196:199], v[104:107]
	v_mfma_f32_16x16x32_bf16 v[108:111], v[132:135], v[196:199], v[108:111]
	v_mfma_f32_16x16x32_bf16 v[108:111], v[128:131], v[192:195], v[108:111]
	v_mfma_f32_16x16x32_bf16 v[92:95], v[128:131], v[200:203], v[92:95]
	v_mfma_f32_16x16x32_bf16 v[92:95], v[132:135], v[204:207], v[92:95]
	v_mfma_f32_16x16x32_bf16 v[88:91], v[140:143], v[204:207], v[88:91]
	v_mfma_f32_16x16x32_bf16 v[88:91], v[136:139], v[200:203], v[88:91]
	v_mfma_f32_16x16x32_bf16 v[84:87], v[144:147], v[200:203], v[84:87]
	v_mfma_f32_16x16x32_bf16 v[84:87], v[148:151], v[204:207], v[84:87]
	v_mfma_f32_16x16x32_bf16 v[80:83], v[174:177], v[204:207], v[80:83]
	v_mfma_f32_16x16x32_bf16 v[80:83], v[170:173], v[200:203], v[80:83]
	v_mfma_f32_16x16x32_bf16 v[64:67], v[170:173], v[208:211], v[64:67]
	v_mfma_f32_16x16x32_bf16 v[64:67], v[174:177], v[212:215], v[64:67]
	v_mfma_f32_16x16x32_bf16 v[68:71], v[148:151], v[212:215], v[68:71]
	v_mfma_f32_16x16x32_bf16 v[68:71], v[144:147], v[208:211], v[68:71]
	v_mfma_f32_16x16x32_bf16 v[72:75], v[136:139], v[208:211], v[72:75]
	v_mfma_f32_16x16x32_bf16 v[72:75], v[140:143], v[212:215], v[72:75]
	v_mfma_f32_16x16x32_bf16 v[76:79], v[132:135], v[212:215], v[76:79]
	v_mfma_f32_16x16x32_bf16 v[76:79], v[128:131], v[208:211], v[76:79]
	s_barrier
	s_add_i32 s54, s50, s39
	v_lshl_add_u64 v[216:217], s[26:27], 0, v[154:155]
	s_mov_b32 m0, s54
	v_lshl_add_u64 v[218:219], s[26:27], 0, v[158:159]
	global_load_lds_dwordx4 v[216:217], off sc0
	s_add_i32 m0, s54, 0x2000
	s_add_u32 s54, s26, 0x100000
	s_addc_u32 s55, s27, 0
	s_add_i32 s56, s51, s39
	global_load_lds_dwordx4 v[218:219], off sc0
	v_lshl_add_u64 v[184:185], s[54:55], 0, v[154:155]
	s_mov_b32 m0, s56
	v_lshl_add_u64 v[220:221], s[28:29], 0, v[152:153]
	global_load_lds_dwordx4 v[184:185], off sc0
	v_lshl_add_u64 v[184:185], s[54:55], 0, v[158:159]
	s_add_i32 m0, s56, 0x2000
	v_lshl_add_u64 v[222:223], s[28:29], 0, v[156:157]
	global_load_lds_dwordx4 v[184:185], off sc0
	s_mov_b32 m0, s40
	s_nop 0
	global_load_lds_dwordx4 v[220:221], off sc0
	s_mov_b32 m0, s41
	s_nop 0
	global_load_lds_dwordx4 v[222:223], off sc0
	ds_read_b128 v[184:187], v182 offset:16384
	ds_read_b128 v[188:191], v182 offset:17408
	ds_read_b128 v[192:195], v182 offset:18432
	ds_read_b128 v[196:199], v182 offset:19456
	ds_read_b128 v[200:203], v182 offset:20480
	ds_read_b128 v[204:207], v182 offset:21504
	ds_read_b128 v[208:211], v182 offset:22528
	ds_read_b128 v[212:215], v182 offset:23552
	s_waitcnt vmcnt(8)
	s_waitcnt lgkmcnt(0)
	s_barrier
	v_mfma_f32_16x16x32_bf16 v[60:63], v[128:131], v[184:187], v[60:63]
	v_mfma_f32_16x16x32_bf16 v[60:63], v[132:135], v[188:191], v[60:63]
	v_mfma_f32_16x16x32_bf16 v[56:59], v[140:143], v[188:191], v[56:59]
	v_mfma_f32_16x16x32_bf16 v[56:59], v[136:139], v[184:187], v[56:59]
	v_mfma_f32_16x16x32_bf16 v[52:55], v[144:147], v[184:187], v[52:55]
	v_mfma_f32_16x16x32_bf16 v[52:55], v[148:151], v[188:191], v[52:55]
	v_mfma_f32_16x16x32_bf16 v[48:51], v[174:177], v[188:191], v[48:51]
	v_mfma_f32_16x16x32_bf16 v[48:51], v[170:173], v[184:187], v[48:51]
	v_mfma_f32_16x16x32_bf16 v[32:35], v[170:173], v[192:195], v[32:35]
	v_mfma_f32_16x16x32_bf16 v[32:35], v[174:177], v[196:199], v[32:35]
	v_mfma_f32_16x16x32_bf16 v[36:39], v[148:151], v[196:199], v[36:39]
	v_mfma_f32_16x16x32_bf16 v[36:39], v[144:147], v[192:195], v[36:39]
	v_mfma_f32_16x16x32_bf16 v[40:43], v[136:139], v[192:195], v[40:43]
	v_mfma_f32_16x16x32_bf16 v[40:43], v[140:143], v[196:199], v[40:43]
	v_mfma_f32_16x16x32_bf16 v[44:47], v[132:135], v[196:199], v[44:47]
	v_mfma_f32_16x16x32_bf16 v[44:47], v[128:131], v[192:195], v[44:47]
	v_mfma_f32_16x16x32_bf16 v[28:31], v[128:131], v[200:203], v[28:31]
	v_mfma_f32_16x16x32_bf16 v[28:31], v[132:135], v[204:207], v[28:31]
	v_mfma_f32_16x16x32_bf16 v[24:27], v[140:143], v[204:207], v[24:27]
	v_mfma_f32_16x16x32_bf16 v[24:27], v[136:139], v[200:203], v[24:27]
	v_mfma_f32_16x16x32_bf16 v[20:23], v[144:147], v[200:203], v[20:23]
	v_mfma_f32_16x16x32_bf16 v[20:23], v[148:151], v[204:207], v[20:23]
	v_mfma_f32_16x16x32_bf16 v[16:19], v[174:177], v[204:207], v[16:19]
	v_mfma_f32_16x16x32_bf16 v[16:19], v[170:173], v[200:203], v[16:19]
	v_mfma_f32_16x16x32_bf16 v[0:3], v[170:173], v[208:211], v[0:3]
	v_mfma_f32_16x16x32_bf16 v[0:3], v[174:177], v[212:215], v[0:3]
	v_mfma_f32_16x16x32_bf16 v[4:7], v[148:151], v[212:215], v[4:7]
	v_mfma_f32_16x16x32_bf16 v[4:7], v[144:147], v[208:211], v[4:7]
	v_mfma_f32_16x16x32_bf16 v[8:11], v[136:139], v[208:211], v[8:11]
	v_mfma_f32_16x16x32_bf16 v[8:11], v[140:143], v[212:215], v[8:11]
	v_mfma_f32_16x16x32_bf16 v[12:15], v[132:135], v[212:215], v[12:15]
	v_mfma_f32_16x16x32_bf16 v[12:15], v[128:131], v[208:211], v[12:15]
	s_barrier
	s_add_i32 s54, 0, 0x18000
	s_add_i32 s55, 0, 0x1c000
	v_add_u32_e32 v140, s54, v178
	v_add_u32_e32 v174, s55, v178
	ds_read_b128 v[128:131], v140
	ds_read_b128 v[132:135], v140 offset:1024
	ds_read_b128 v[136:139], v140 offset:2048
	ds_read_b128 v[140:143], v140 offset:3072
	ds_read_b128 v[144:147], v174
	ds_read_b128 v[148:151], v174 offset:1024
	ds_read_b128 v[170:173], v174 offset:2048
	ds_read_b128 v[174:177], v174 offset:3072
	s_add_u32 s28, s28, 0x40000
	s_addc_u32 s29, s29, 0
	s_mov_b32 m0, s42
	v_lshl_add_u64 v[184:185], s[28:29], 0, v[152:153]
	global_load_lds_dwordx4 v[184:185], off sc0
	v_lshl_add_u64 v[184:185], s[28:29], 0, v[156:157]
	s_mov_b32 m0, s43
	s_nop 0
	global_load_lds_dwordx4 v[184:185], off sc0
	ds_read_b128 v[184:187], v182 offset:32768
	ds_read_b128 v[188:191], v182 offset:33792
	ds_read_b128 v[192:195], v182 offset:34816
	ds_read_b128 v[196:199], v182 offset:35840
	ds_read_b128 v[200:203], v182 offset:36864
	ds_read_b128 v[204:207], v182 offset:37888
	ds_read_b128 v[208:211], v182 offset:38912
	ds_read_b128 v[212:215], v182 offset:39936
	s_waitcnt vmcnt(8)
	s_waitcnt lgkmcnt(0)
	s_barrier
	v_mfma_f32_16x16x32_bf16 v[124:127], v[128:131], v[184:187], v[124:127]
	v_mfma_f32_16x16x32_bf16 v[124:127], v[132:135], v[188:191], v[124:127]
	v_mfma_f32_16x16x32_bf16 v[120:123], v[140:143], v[188:191], v[120:123]
	v_mfma_f32_16x16x32_bf16 v[120:123], v[136:139], v[184:187], v[120:123]
	v_mfma_f32_16x16x32_bf16 v[116:119], v[144:147], v[184:187], v[116:119]
	v_mfma_f32_16x16x32_bf16 v[116:119], v[148:151], v[188:191], v[116:119]
	v_mfma_f32_16x16x32_bf16 v[112:115], v[174:177], v[188:191], v[112:115]
	v_mfma_f32_16x16x32_bf16 v[112:115], v[170:173], v[184:187], v[112:115]
	v_mfma_f32_16x16x32_bf16 v[96:99], v[170:173], v[192:195], v[96:99]
	v_mfma_f32_16x16x32_bf16 v[96:99], v[174:177], v[196:199], v[96:99]
	v_mfma_f32_16x16x32_bf16 v[100:103], v[148:151], v[196:199], v[100:103]
	v_mfma_f32_16x16x32_bf16 v[100:103], v[144:147], v[192:195], v[100:103]
	v_mfma_f32_16x16x32_bf16 v[104:107], v[136:139], v[192:195], v[104:107]
	v_mfma_f32_16x16x32_bf16 v[104:107], v[140:143], v[196:199], v[104:107]
	v_mfma_f32_16x16x32_bf16 v[108:111], v[132:135], v[196:199], v[108:111]
	v_mfma_f32_16x16x32_bf16 v[108:111], v[128:131], v[192:195], v[108:111]
	v_mfma_f32_16x16x32_bf16 v[92:95], v[128:131], v[200:203], v[92:95]
	v_mfma_f32_16x16x32_bf16 v[92:95], v[132:135], v[204:207], v[92:95]
	v_mfma_f32_16x16x32_bf16 v[88:91], v[140:143], v[204:207], v[88:91]
	v_mfma_f32_16x16x32_bf16 v[88:91], v[136:139], v[200:203], v[88:91]
	v_mfma_f32_16x16x32_bf16 v[84:87], v[144:147], v[200:203], v[84:87]
	v_mfma_f32_16x16x32_bf16 v[84:87], v[148:151], v[204:207], v[84:87]
	v_mfma_f32_16x16x32_bf16 v[80:83], v[174:177], v[204:207], v[80:83]
	v_mfma_f32_16x16x32_bf16 v[80:83], v[170:173], v[200:203], v[80:83]
	v_mfma_f32_16x16x32_bf16 v[64:67], v[170:173], v[208:211], v[64:67]
	v_mfma_f32_16x16x32_bf16 v[64:67], v[174:177], v[212:215], v[64:67]
	v_mfma_f32_16x16x32_bf16 v[68:71], v[148:151], v[212:215], v[68:71]
	v_mfma_f32_16x16x32_bf16 v[68:71], v[144:147], v[208:211], v[68:71]
	v_mfma_f32_16x16x32_bf16 v[72:75], v[136:139], v[208:211], v[72:75]
	v_mfma_f32_16x16x32_bf16 v[72:75], v[140:143], v[212:215], v[72:75]
	v_mfma_f32_16x16x32_bf16 v[76:79], v[132:135], v[212:215], v[76:79]
	v_mfma_f32_16x16x32_bf16 v[76:79], v[128:131], v[208:211], v[76:79]
	s_barrier
	s_add_i32 s28, s54, s39
	v_lshl_add_u64 v[184:185], v[216:217], 0, s[14:15]
	s_mov_b32 m0, s28
	s_nop 0
	global_load_lds_dwordx4 v[184:185], off sc0
	s_add_i32 m0, s28, 0x2000
	s_add_u32 s26, s26, 0x100080
	v_lshl_add_u64 v[184:185], v[218:219], 0, s[14:15]
	s_addc_u32 s27, s27, 0
	s_add_i32 s28, s55, s39
	global_load_lds_dwordx4 v[184:185], off sc0
	v_lshl_add_u64 v[184:185], s[26:27], 0, v[154:155]
	s_mov_b32 m0, s28
	s_nop 0
	global_load_lds_dwordx4 v[184:185], off sc0
	v_lshl_add_u64 v[184:185], s[26:27], 0, v[158:159]
	s_add_i32 m0, s28, 0x2000
	s_nop 0
	global_load_lds_dwordx4 v[184:185], off sc0
	v_lshl_add_u64 v[184:185], v[220:221], 0, s[14:15]
	s_mov_b32 m0, s45
	s_nop 0
	global_load_lds_dwordx4 v[184:185], off sc0
	v_lshl_add_u64 v[184:185], v[222:223], 0, s[14:15]
	s_mov_b32 m0, s46
	s_nop 0
	global_load_lds_dwordx4 v[184:185], off sc0
	ds_read_b128 v[184:187], v182 offset:49152
	ds_read_b128 v[188:191], v182 offset:50176
	ds_read_b128 v[192:195], v182 offset:51200
	ds_read_b128 v[196:199], v182 offset:52224
	ds_read_b128 v[200:203], v182 offset:53248
	ds_read_b128 v[204:207], v182 offset:54272
	ds_read_b128 v[208:211], v182 offset:55296
	ds_read_b128 v[212:215], v182 offset:56320
	s_waitcnt vmcnt(8)
	s_waitcnt lgkmcnt(0)
	s_barrier
	v_mfma_f32_16x16x32_bf16 v[60:63], v[128:131], v[184:187], v[60:63]
	v_mfma_f32_16x16x32_bf16 v[60:63], v[132:135], v[188:191], v[60:63]
	v_mfma_f32_16x16x32_bf16 v[56:59], v[140:143], v[188:191], v[56:59]
	v_mfma_f32_16x16x32_bf16 v[56:59], v[136:139], v[184:187], v[56:59]
	v_mfma_f32_16x16x32_bf16 v[52:55], v[144:147], v[184:187], v[52:55]
	v_mfma_f32_16x16x32_bf16 v[52:55], v[148:151], v[188:191], v[52:55]
	v_mfma_f32_16x16x32_bf16 v[48:51], v[174:177], v[188:191], v[48:51]
	v_mfma_f32_16x16x32_bf16 v[48:51], v[170:173], v[184:187], v[48:51]
	v_mfma_f32_16x16x32_bf16 v[32:35], v[170:173], v[192:195], v[32:35]
	v_mfma_f32_16x16x32_bf16 v[32:35], v[174:177], v[196:199], v[32:35]
	v_mfma_f32_16x16x32_bf16 v[36:39], v[148:151], v[196:199], v[36:39]
	v_mfma_f32_16x16x32_bf16 v[36:39], v[144:147], v[192:195], v[36:39]
	v_mfma_f32_16x16x32_bf16 v[40:43], v[136:139], v[192:195], v[40:43]
	v_mfma_f32_16x16x32_bf16 v[40:43], v[140:143], v[196:199], v[40:43]
	v_mfma_f32_16x16x32_bf16 v[44:47], v[132:135], v[196:199], v[44:47]
	v_mfma_f32_16x16x32_bf16 v[44:47], v[128:131], v[192:195], v[44:47]
	v_mfma_f32_16x16x32_bf16 v[28:31], v[128:131], v[200:203], v[28:31]
	v_mfma_f32_16x16x32_bf16 v[28:31], v[132:135], v[204:207], v[28:31]
	v_mfma_f32_16x16x32_bf16 v[24:27], v[140:143], v[204:207], v[24:27]
	v_mfma_f32_16x16x32_bf16 v[24:27], v[136:139], v[200:203], v[24:27]
	v_mfma_f32_16x16x32_bf16 v[20:23], v[144:147], v[200:203], v[20:23]
	v_mfma_f32_16x16x32_bf16 v[20:23], v[148:151], v[204:207], v[20:23]
	v_mfma_f32_16x16x32_bf16 v[16:19], v[174:177], v[204:207], v[16:19]
	v_mfma_f32_16x16x32_bf16 v[16:19], v[170:173], v[200:203], v[16:19]
	v_mfma_f32_16x16x32_bf16 v[0:3], v[170:173], v[208:211], v[0:3]
	v_mfma_f32_16x16x32_bf16 v[0:3], v[174:177], v[212:215], v[0:3]
	v_mfma_f32_16x16x32_bf16 v[4:7], v[148:151], v[212:215], v[4:7]
	v_mfma_f32_16x16x32_bf16 v[4:7], v[144:147], v[208:211], v[4:7]
	v_mfma_f32_16x16x32_bf16 v[8:11], v[136:139], v[208:211], v[8:11]
	v_mfma_f32_16x16x32_bf16 v[8:11], v[140:143], v[212:215], v[8:11]
	v_mfma_f32_16x16x32_bf16 v[12:15], v[132:135], v[212:215], v[12:15]
	v_mfma_f32_16x16x32_bf16 v[12:15], v[128:131], v[208:211], v[12:15]
	s_barrier
	s_add_i32 s35, s35, 2
	s_add_u32 s24, s24, 0x100
	s_addc_u32 s25, s25, 0
	s_add_u32 s31, s31, 0x100
	s_addc_u32 s34, s34, 0
	s_cmp_gt_u32 s35, 13
	s_cbranch_scc0 .LBB0_1435

.LBB0_1543:
	ds_read_b128 v[128:131], v167
	ds_read_b128 v[154:157], v167 offset:1024
	ds_read_b128 v[172:175], v167 offset:2048
	ds_read_b128 v[176:179], v167 offset:3072
	ds_read_b128 v[180:183], v168
	ds_read_b128 v[184:187], v168 offset:1024
	ds_read_b128 v[188:191], v168 offset:2048
	ds_read_b128 v[192:195], v168 offset:3072
	s_add_u32 s22, s20, 0x1000
	s_addc_u32 s23, s21, 0
	s_cmp_eq_u32 s54, 60
	s_cselect_b32 s27, s13, s23
	s_cselect_b32 s26, s50, s22
	s_cselect_b32 s25, s11, s53
	s_cselect_b32 s24, s51, s52
	v_lshl_add_u64 v[160:161], s[20:21], 0, v[144:145]
	s_add_i32 m0, s19, 0xc000
	s_nop 0
	global_load_lds_dwordx4 v[160:161], off sc0
	v_lshl_add_u64 v[160:161], s[20:21], 0, v[146:147]
	s_add_i32 m0, s19, 0xe000
	s_nop 0
	global_load_lds_dwordx4 v[160:161], off sc0
	ds_read_b128 v[196:199], v169
	ds_read_b128 v[200:203], v169 offset:1024
	ds_read_b128 v[204:207], v169 offset:2048
	ds_read_b128 v[208:211], v169 offset:3072
	ds_read_b128 v[212:215], v169 offset:4096
	ds_read_b128 v[216:219], v169 offset:5120
	ds_read_b128 v[220:223], v169 offset:6144
	ds_read_b128 v[224:227], v169 offset:7168
	s_waitcnt vmcnt(8)
	s_waitcnt lgkmcnt(0)
	s_barrier
	v_mfma_f32_16x16x32_bf16 v[124:127], v[128:131], v[196:199], v[124:127]
	v_mfma_f32_16x16x32_bf16 v[124:127], v[154:157], v[200:203], v[124:127]
	v_mfma_f32_16x16x32_bf16 v[120:123], v[176:179], v[200:203], v[120:123]
	v_mfma_f32_16x16x32_bf16 v[120:123], v[172:175], v[196:199], v[120:123]
	v_mfma_f32_16x16x32_bf16 v[116:119], v[180:183], v[196:199], v[116:119]
	v_mfma_f32_16x16x32_bf16 v[116:119], v[184:187], v[200:203], v[116:119]
	v_mfma_f32_16x16x32_bf16 v[112:115], v[192:195], v[200:203], v[112:115]
	v_mfma_f32_16x16x32_bf16 v[112:115], v[188:191], v[196:199], v[112:115]
	v_mfma_f32_16x16x32_bf16 v[96:99], v[188:191], v[204:207], v[96:99]
	v_mfma_f32_16x16x32_bf16 v[96:99], v[192:195], v[208:211], v[96:99]
	v_mfma_f32_16x16x32_bf16 v[100:103], v[184:187], v[208:211], v[100:103]
	v_mfma_f32_16x16x32_bf16 v[100:103], v[180:183], v[204:207], v[100:103]
	v_mfma_f32_16x16x32_bf16 v[104:107], v[172:175], v[204:207], v[104:107]
	v_mfma_f32_16x16x32_bf16 v[104:107], v[176:179], v[208:211], v[104:107]
	v_mfma_f32_16x16x32_bf16 v[108:111], v[154:157], v[208:211], v[108:111]
	v_mfma_f32_16x16x32_bf16 v[108:111], v[128:131], v[204:207], v[108:111]
	v_mfma_f32_16x16x32_bf16 v[92:95], v[128:131], v[212:215], v[92:95]
	v_mfma_f32_16x16x32_bf16 v[92:95], v[154:157], v[216:219], v[92:95]
	v_mfma_f32_16x16x32_bf16 v[88:91], v[176:179], v[216:219], v[88:91]
	v_mfma_f32_16x16x32_bf16 v[88:91], v[172:175], v[212:215], v[88:91]
	v_mfma_f32_16x16x32_bf16 v[84:87], v[180:183], v[212:215], v[84:87]
	v_mfma_f32_16x16x32_bf16 v[84:87], v[184:187], v[216:219], v[84:87]
	v_mfma_f32_16x16x32_bf16 v[80:83], v[192:195], v[216:219], v[80:83]
	v_mfma_f32_16x16x32_bf16 v[80:83], v[188:191], v[212:215], v[80:83]
	v_mfma_f32_16x16x32_bf16 v[64:67], v[188:191], v[220:223], v[64:67]
	v_mfma_f32_16x16x32_bf16 v[64:67], v[192:195], v[224:227], v[64:67]
	v_mfma_f32_16x16x32_bf16 v[68:71], v[184:187], v[224:227], v[68:71]
	v_mfma_f32_16x16x32_bf16 v[68:71], v[180:183], v[220:223], v[68:71]
	v_mfma_f32_16x16x32_bf16 v[72:75], v[172:175], v[220:223], v[72:75]
	v_mfma_f32_16x16x32_bf16 v[72:75], v[176:179], v[224:227], v[72:75]
	v_mfma_f32_16x16x32_bf16 v[76:79], v[154:157], v[224:227], v[76:79]
	v_mfma_f32_16x16x32_bf16 v[76:79], v[128:131], v[220:223], v[76:79]
	s_barrier
	s_add_i32 s20, s45, s30
	v_lshl_add_u64 v[160:161], s[24:25], 0, v[134:135]
	s_mov_b32 m0, s20
	v_lshl_add_u64 v[164:165], s[24:25], 0, v[138:139]
	global_load_lds_dwordx4 v[160:161], off sc0
	s_add_i32 m0, s20, 0x2000
	s_add_u32 s20, s24, 0x100000
	s_addc_u32 s21, s25, 0
	s_add_i32 s55, s46, s30
	global_load_lds_dwordx4 v[164:165], off sc0
	v_lshl_add_u64 v[196:197], s[20:21], 0, v[134:135]
	s_mov_b32 m0, s55
	v_lshl_add_u64 v[228:229], s[26:27], 0, v[132:133]
	global_load_lds_dwordx4 v[196:197], off sc0
	v_lshl_add_u64 v[196:197], s[20:21], 0, v[138:139]
	s_add_i32 m0, s55, 0x2000
	v_lshl_add_u64 v[230:231], s[26:27], 0, v[136:137]
	global_load_lds_dwordx4 v[196:197], off sc0
	s_mov_b32 m0, s19
	s_nop 0
	global_load_lds_dwordx4 v[228:229], off sc0
	s_mov_b32 m0, s36
	s_nop 0
	global_load_lds_dwordx4 v[230:231], off sc0
	ds_read_b128 v[196:199], v169 offset:16384
	ds_read_b128 v[200:203], v169 offset:17408
	ds_read_b128 v[204:207], v169 offset:18432
	ds_read_b128 v[208:211], v169 offset:19456
	ds_read_b128 v[212:215], v169 offset:20480
	ds_read_b128 v[216:219], v169 offset:21504
	ds_read_b128 v[220:223], v169 offset:22528
	ds_read_b128 v[224:227], v169 offset:23552
	s_waitcnt vmcnt(8)
	s_waitcnt lgkmcnt(0)
	s_barrier
	v_mfma_f32_16x16x32_bf16 v[60:63], v[128:131], v[196:199], v[60:63]
	v_mfma_f32_16x16x32_bf16 v[60:63], v[154:157], v[200:203], v[60:63]
	v_mfma_f32_16x16x32_bf16 v[56:59], v[176:179], v[200:203], v[56:59]
	v_mfma_f32_16x16x32_bf16 v[56:59], v[172:175], v[196:199], v[56:59]
	v_mfma_f32_16x16x32_bf16 v[52:55], v[180:183], v[196:199], v[52:55]
	v_mfma_f32_16x16x32_bf16 v[52:55], v[184:187], v[200:203], v[52:55]
	v_mfma_f32_16x16x32_bf16 v[48:51], v[192:195], v[200:203], v[48:51]
	v_mfma_f32_16x16x32_bf16 v[48:51], v[188:191], v[196:199], v[48:51]
	v_mfma_f32_16x16x32_bf16 v[32:35], v[188:191], v[204:207], v[32:35]
	v_mfma_f32_16x16x32_bf16 v[32:35], v[192:195], v[208:211], v[32:35]
	v_mfma_f32_16x16x32_bf16 v[36:39], v[184:187], v[208:211], v[36:39]
	v_mfma_f32_16x16x32_bf16 v[36:39], v[180:183], v[204:207], v[36:39]
	v_mfma_f32_16x16x32_bf16 v[40:43], v[172:175], v[204:207], v[40:43]
	v_mfma_f32_16x16x32_bf16 v[40:43], v[176:179], v[208:211], v[40:43]
	v_mfma_f32_16x16x32_bf16 v[44:47], v[154:157], v[208:211], v[44:47]
	v_mfma_f32_16x16x32_bf16 v[44:47], v[128:131], v[204:207], v[44:47]
	v_mfma_f32_16x16x32_bf16 v[28:31], v[128:131], v[212:215], v[28:31]
	v_mfma_f32_16x16x32_bf16 v[28:31], v[154:157], v[216:219], v[28:31]
	v_mfma_f32_16x16x32_bf16 v[24:27], v[176:179], v[216:219], v[24:27]
	v_mfma_f32_16x16x32_bf16 v[24:27], v[172:175], v[212:215], v[24:27]
	v_mfma_f32_16x16x32_bf16 v[20:23], v[180:183], v[212:215], v[20:23]
	v_mfma_f32_16x16x32_bf16 v[20:23], v[184:187], v[216:219], v[20:23]
	v_mfma_f32_16x16x32_bf16 v[16:19], v[192:195], v[216:219], v[16:19]
	v_mfma_f32_16x16x32_bf16 v[16:19], v[188:191], v[212:215], v[16:19]
	v_mfma_f32_16x16x32_bf16 v[0:3], v[188:191], v[220:223], v[0:3]
	v_mfma_f32_16x16x32_bf16 v[0:3], v[192:195], v[224:227], v[0:3]
	v_mfma_f32_16x16x32_bf16 v[4:7], v[184:187], v[224:227], v[4:7]
	v_mfma_f32_16x16x32_bf16 v[4:7], v[180:183], v[220:223], v[4:7]
	v_mfma_f32_16x16x32_bf16 v[8:11], v[172:175], v[220:223], v[8:11]
	v_mfma_f32_16x16x32_bf16 v[8:11], v[176:179], v[224:227], v[8:11]
	v_mfma_f32_16x16x32_bf16 v[12:15], v[154:157], v[224:227], v[12:15]
	v_mfma_f32_16x16x32_bf16 v[12:15], v[128:131], v[220:223], v[12:15]
	s_barrier
	s_add_i32 s55, 0, 0x18000
	v_add_u32_e32 v153, s55, v159
	s_add_i32 s56, 0, 0x1c000
	ds_read_b128 v[128:131], v153
	ds_read_b128 v[154:157], v153 offset:1024
	ds_read_b128 v[172:175], v153 offset:2048
	ds_read_b128 v[176:179], v153 offset:3072
	v_add_u32_e32 v153, s56, v159
	ds_read_b128 v[180:183], v153
	ds_read_b128 v[184:187], v153 offset:1024
	ds_read_b128 v[188:191], v153 offset:2048
	ds_read_b128 v[192:195], v153 offset:3072
	s_add_u32 s20, s26, 0x100000
	s_addc_u32 s21, s27, 0
	s_mov_b32 m0, s37
	v_lshl_add_u64 v[196:197], s[20:21], 0, v[132:133]
	global_load_lds_dwordx4 v[196:197], off sc0
	v_lshl_add_u64 v[196:197], s[20:21], 0, v[136:137]
	s_mov_b32 m0, s38
	s_nop 0
	global_load_lds_dwordx4 v[196:197], off sc0
	ds_read_b128 v[196:199], v169 offset:32768
	ds_read_b128 v[200:203], v169 offset:33792
	ds_read_b128 v[204:207], v169 offset:34816
	ds_read_b128 v[208:211], v169 offset:35840
	ds_read_b128 v[212:215], v169 offset:36864
	ds_read_b128 v[216:219], v169 offset:37888
	ds_read_b128 v[220:223], v169 offset:38912
	ds_read_b128 v[224:227], v169 offset:39936
	s_waitcnt vmcnt(8)
	s_waitcnt lgkmcnt(0)
	s_barrier
	v_mfma_f32_16x16x32_bf16 v[124:127], v[128:131], v[196:199], v[124:127]
	v_mfma_f32_16x16x32_bf16 v[124:127], v[154:157], v[200:203], v[124:127]
	v_mfma_f32_16x16x32_bf16 v[120:123], v[176:179], v[200:203], v[120:123]
	v_mfma_f32_16x16x32_bf16 v[120:123], v[172:175], v[196:199], v[120:123]
	v_mfma_f32_16x16x32_bf16 v[116:119], v[180:183], v[196:199], v[116:119]
	v_mfma_f32_16x16x32_bf16 v[116:119], v[184:187], v[200:203], v[116:119]
	v_mfma_f32_16x16x32_bf16 v[112:115], v[192:195], v[200:203], v[112:115]
	v_mfma_f32_16x16x32_bf16 v[112:115], v[188:191], v[196:199], v[112:115]
	v_mfma_f32_16x16x32_bf16 v[96:99], v[188:191], v[204:207], v[96:99]
	v_mfma_f32_16x16x32_bf16 v[96:99], v[192:195], v[208:211], v[96:99]
	v_mfma_f32_16x16x32_bf16 v[100:103], v[184:187], v[208:211], v[100:103]
	v_mfma_f32_16x16x32_bf16 v[100:103], v[180:183], v[204:207], v[100:103]
	v_mfma_f32_16x16x32_bf16 v[104:107], v[172:175], v[204:207], v[104:107]
	v_mfma_f32_16x16x32_bf16 v[104:107], v[176:179], v[208:211], v[104:107]
	v_mfma_f32_16x16x32_bf16 v[108:111], v[154:157], v[208:211], v[108:111]
	v_mfma_f32_16x16x32_bf16 v[108:111], v[128:131], v[204:207], v[108:111]
	v_mfma_f32_16x16x32_bf16 v[92:95], v[128:131], v[212:215], v[92:95]
	v_mfma_f32_16x16x32_bf16 v[92:95], v[154:157], v[216:219], v[92:95]
	v_mfma_f32_16x16x32_bf16 v[88:91], v[176:179], v[216:219], v[88:91]
	v_mfma_f32_16x16x32_bf16 v[88:91], v[172:175], v[212:215], v[88:91]
	v_mfma_f32_16x16x32_bf16 v[84:87], v[180:183], v[212:215], v[84:87]
	v_mfma_f32_16x16x32_bf16 v[84:87], v[184:187], v[216:219], v[84:87]
	v_mfma_f32_16x16x32_bf16 v[80:83], v[192:195], v[216:219], v[80:83]
	v_mfma_f32_16x16x32_bf16 v[80:83], v[188:191], v[212:215], v[80:83]
	v_mfma_f32_16x16x32_bf16 v[64:67], v[188:191], v[220:223], v[64:67]
	v_mfma_f32_16x16x32_bf16 v[64:67], v[192:195], v[224:227], v[64:67]
	v_mfma_f32_16x16x32_bf16 v[68:71], v[184:187], v[224:227], v[68:71]
	v_mfma_f32_16x16x32_bf16 v[68:71], v[180:183], v[220:223], v[68:71]
	v_mfma_f32_16x16x32_bf16 v[72:75], v[172:175], v[220:223], v[72:75]
	v_mfma_f32_16x16x32_bf16 v[72:75], v[176:179], v[224:227], v[72:75]
	v_mfma_f32_16x16x32_bf16 v[76:79], v[154:157], v[224:227], v[76:79]
	v_mfma_f32_16x16x32_bf16 v[76:79], v[128:131], v[220:223], v[76:79]
	s_barrier
	s_add_i32 s20, s55, s30
	v_lshl_add_u64 v[160:161], v[160:161], 0, s[8:9]
	s_mov_b32 m0, s20
	s_nop 0
	global_load_lds_dwordx4 v[160:161], off sc0
	s_add_i32 m0, s20, 0x2000
	s_add_u32 s20, s24, 0x100800
	v_lshl_add_u64 v[160:161], v[164:165], 0, s[8:9]
	s_addc_u32 s21, s25, 0
	s_add_i32 s24, s56, s30
	global_load_lds_dwordx4 v[160:161], off sc0
	v_lshl_add_u64 v[160:161], s[20:21], 0, v[134:135]
	s_mov_b32 m0, s24
	s_nop 0
	global_load_lds_dwordx4 v[160:161], off sc0
	v_lshl_add_u64 v[160:161], s[20:21], 0, v[138:139]
	s_add_i32 m0, s24, 0x2000
	s_nop 0
	global_load_lds_dwordx4 v[160:161], off sc0
	v_lshl_add_u64 v[160:161], v[228:229], 0, s[8:9]
	s_mov_b32 m0, s41
	s_nop 0
	global_load_lds_dwordx4 v[160:161], off sc0
	v_lshl_add_u64 v[160:161], v[230:231], 0, s[8:9]
	s_mov_b32 m0, s42
	s_nop 0
	global_load_lds_dwordx4 v[160:161], off sc0
	ds_read_b128 v[196:199], v169 offset:49152
	ds_read_b128 v[200:203], v169 offset:50176
	ds_read_b128 v[204:207], v169 offset:51200
	ds_read_b128 v[208:211], v169 offset:52224
	ds_read_b128 v[212:215], v169 offset:53248
	ds_read_b128 v[216:219], v169 offset:54272
	ds_read_b128 v[220:223], v169 offset:55296
	ds_read_b128 v[224:227], v169 offset:56320
	s_waitcnt vmcnt(8)
	s_waitcnt lgkmcnt(0)
	s_barrier
	v_mfma_f32_16x16x32_bf16 v[60:63], v[128:131], v[196:199], v[60:63]
	v_mfma_f32_16x16x32_bf16 v[60:63], v[154:157], v[200:203], v[60:63]
	v_mfma_f32_16x16x32_bf16 v[56:59], v[176:179], v[200:203], v[56:59]
	v_mfma_f32_16x16x32_bf16 v[56:59], v[172:175], v[196:199], v[56:59]
	v_mfma_f32_16x16x32_bf16 v[52:55], v[180:183], v[196:199], v[52:55]
	v_mfma_f32_16x16x32_bf16 v[52:55], v[184:187], v[200:203], v[52:55]
	v_mfma_f32_16x16x32_bf16 v[48:51], v[192:195], v[200:203], v[48:51]
	v_mfma_f32_16x16x32_bf16 v[48:51], v[188:191], v[196:199], v[48:51]
	v_mfma_f32_16x16x32_bf16 v[32:35], v[188:191], v[204:207], v[32:35]
	v_mfma_f32_16x16x32_bf16 v[32:35], v[192:195], v[208:211], v[32:35]
	v_mfma_f32_16x16x32_bf16 v[36:39], v[184:187], v[208:211], v[36:39]
	v_mfma_f32_16x16x32_bf16 v[36:39], v[180:183], v[204:207], v[36:39]
	v_mfma_f32_16x16x32_bf16 v[40:43], v[172:175], v[204:207], v[40:43]
	v_mfma_f32_16x16x32_bf16 v[40:43], v[176:179], v[208:211], v[40:43]
	v_mfma_f32_16x16x32_bf16 v[44:47], v[154:157], v[208:211], v[44:47]
	v_mfma_f32_16x16x32_bf16 v[44:47], v[128:131], v[204:207], v[44:47]
	v_mfma_f32_16x16x32_bf16 v[28:31], v[128:131], v[212:215], v[28:31]
	v_mfma_f32_16x16x32_bf16 v[28:31], v[154:157], v[216:219], v[28:31]
	v_mfma_f32_16x16x32_bf16 v[24:27], v[176:179], v[216:219], v[24:27]
	v_mfma_f32_16x16x32_bf16 v[24:27], v[172:175], v[212:215], v[24:27]
	v_mfma_f32_16x16x32_bf16 v[20:23], v[180:183], v[212:215], v[20:23]
	v_mfma_f32_16x16x32_bf16 v[20:23], v[184:187], v[216:219], v[20:23]
	v_mfma_f32_16x16x32_bf16 v[16:19], v[192:195], v[216:219], v[16:19]
	v_mfma_f32_16x16x32_bf16 v[16:19], v[188:191], v[212:215], v[16:19]
	v_mfma_f32_16x16x32_bf16 v[0:3], v[188:191], v[220:223], v[0:3]
	v_mfma_f32_16x16x32_bf16 v[0:3], v[192:195], v[224:227], v[0:3]
	v_mfma_f32_16x16x32_bf16 v[4:7], v[184:187], v[224:227], v[4:7]
	v_mfma_f32_16x16x32_bf16 v[4:7], v[180:183], v[220:223], v[4:7]
	v_mfma_f32_16x16x32_bf16 v[8:11], v[172:175], v[220:223], v[8:11]
	v_mfma_f32_16x16x32_bf16 v[8:11], v[176:179], v[224:227], v[8:11]
	v_mfma_f32_16x16x32_bf16 v[12:15], v[154:157], v[224:227], v[12:15]
	v_mfma_f32_16x16x32_bf16 v[12:15], v[128:131], v[220:223], v[12:15]
	s_barrier
	s_add_i32 s54, s54, 2
	s_add_u32 s52, s52, 0x1000
	s_addc_u32 s53, s53, 0
	s_cmp_gt_u32 s54, 61
	s_mov_b64 s[20:21], s[22:23]
	s_cbranch_scc0 .LBB0_1543

.LBB0_1625:
	ds_read_b128 v[128:131], v177
	ds_read_b128 v[132:135], v177 offset:1024
	ds_read_b128 v[136:139], v177 offset:2048
	ds_read_b128 v[140:143], v177 offset:3072
	ds_read_b128 v[144:147], v178
	ds_read_b128 v[148:151], v178 offset:1024
	ds_read_b128 v[170:173], v178 offset:2048
	ds_read_b128 v[182:185], v178 offset:3072
	s_add_u32 s24, s22, 0xffc00800
	s_addc_u32 s25, s23, -1
	s_cmpk_eq_i32 s57, 0xfc
	s_cselect_b32 s27, s29, s25
	s_cselect_b32 s26, s53, s24
	s_cselect_b32 s25, s17, s56
	s_cselect_b32 s24, s54, s55
	v_lshl_add_u64 v[186:187], s[22:23], 0, v[162:163]
	s_add_i32 m0, s38, 0xc000
	s_nop 0
	global_load_lds_dwordx4 v[186:187], off sc0
	v_lshl_add_u64 v[186:187], s[22:23], 0, v[164:165]
	s_add_i32 m0, s38, 0xe000
	s_nop 0
	global_load_lds_dwordx4 v[186:187], off sc0
	ds_read_b128 v[186:189], v179
	ds_read_b128 v[190:193], v179 offset:1024
	ds_read_b128 v[194:197], v179 offset:2048
	ds_read_b128 v[198:201], v179 offset:3072
	ds_read_b128 v[202:205], v179 offset:4096
	ds_read_b128 v[206:209], v179 offset:5120
	ds_read_b128 v[210:213], v179 offset:6144
	ds_read_b128 v[214:217], v179 offset:7168
	s_waitcnt vmcnt(8)
	s_waitcnt lgkmcnt(0)
	s_barrier
	v_mfma_f32_16x16x32_bf16 v[124:127], v[128:131], v[186:189], v[124:127]
	v_mfma_f32_16x16x32_bf16 v[124:127], v[132:135], v[190:193], v[124:127]
	v_mfma_f32_16x16x32_bf16 v[120:123], v[140:143], v[190:193], v[120:123]
	v_mfma_f32_16x16x32_bf16 v[120:123], v[136:139], v[186:189], v[120:123]
	v_mfma_f32_16x16x32_bf16 v[116:119], v[144:147], v[186:189], v[116:119]
	v_mfma_f32_16x16x32_bf16 v[116:119], v[148:151], v[190:193], v[116:119]
	v_mfma_f32_16x16x32_bf16 v[112:115], v[182:185], v[190:193], v[112:115]
	v_mfma_f32_16x16x32_bf16 v[112:115], v[170:173], v[186:189], v[112:115]
	v_mfma_f32_16x16x32_bf16 v[96:99], v[170:173], v[194:197], v[96:99]
	v_mfma_f32_16x16x32_bf16 v[96:99], v[182:185], v[198:201], v[96:99]
	v_mfma_f32_16x16x32_bf16 v[100:103], v[148:151], v[198:201], v[100:103]
	v_mfma_f32_16x16x32_bf16 v[100:103], v[144:147], v[194:197], v[100:103]
	v_mfma_f32_16x16x32_bf16 v[104:107], v[136:139], v[194:197], v[104:107]
	v_mfma_f32_16x16x32_bf16 v[104:107], v[140:143], v[198:201], v[104:107]
	v_mfma_f32_16x16x32_bf16 v[108:111], v[132:135], v[198:201], v[108:111]
	v_mfma_f32_16x16x32_bf16 v[108:111], v[128:131], v[194:197], v[108:111]
	v_mfma_f32_16x16x32_bf16 v[92:95], v[128:131], v[202:205], v[92:95]
	v_mfma_f32_16x16x32_bf16 v[92:95], v[132:135], v[206:209], v[92:95]
	v_mfma_f32_16x16x32_bf16 v[88:91], v[140:143], v[206:209], v[88:91]
	v_mfma_f32_16x16x32_bf16 v[88:91], v[136:139], v[202:205], v[88:91]
	v_mfma_f32_16x16x32_bf16 v[84:87], v[144:147], v[202:205], v[84:87]
	v_mfma_f32_16x16x32_bf16 v[84:87], v[148:151], v[206:209], v[84:87]
	v_mfma_f32_16x16x32_bf16 v[80:83], v[182:185], v[206:209], v[80:83]
	v_mfma_f32_16x16x32_bf16 v[80:83], v[170:173], v[202:205], v[80:83]
	v_mfma_f32_16x16x32_bf16 v[64:67], v[170:173], v[210:213], v[64:67]
	v_mfma_f32_16x16x32_bf16 v[64:67], v[182:185], v[214:217], v[64:67]
	v_mfma_f32_16x16x32_bf16 v[68:71], v[148:151], v[214:217], v[68:71]
	v_mfma_f32_16x16x32_bf16 v[68:71], v[144:147], v[210:213], v[68:71]
	v_mfma_f32_16x16x32_bf16 v[72:75], v[136:139], v[210:213], v[72:75]
	v_mfma_f32_16x16x32_bf16 v[72:75], v[140:143], v[214:217], v[72:75]
	v_mfma_f32_16x16x32_bf16 v[76:79], v[132:135], v[214:217], v[76:79]
	v_mfma_f32_16x16x32_bf16 v[76:79], v[128:131], v[210:213], v[76:79]
	s_barrier
	s_add_i32 s58, s48, s37
	v_lshl_add_u64 v[218:219], s[24:25], 0, v[154:155]
	s_mov_b32 m0, s58
	v_lshl_add_u64 v[220:221], s[24:25], 0, v[158:159]
	global_load_lds_dwordx4 v[218:219], off sc0
	s_add_i32 m0, s58, 0x2000
	s_add_u32 s58, s24, 0x400000
	s_addc_u32 s59, s25, 0
	s_add_i32 s60, s49, s37
	global_load_lds_dwordx4 v[220:221], off sc0
	v_lshl_add_u64 v[186:187], s[58:59], 0, v[154:155]
	s_mov_b32 m0, s60
	v_lshl_add_u64 v[222:223], s[26:27], 0, v[152:153]
	global_load_lds_dwordx4 v[186:187], off sc0
	v_lshl_add_u64 v[186:187], s[58:59], 0, v[158:159]
	s_add_i32 m0, s60, 0x2000
	v_lshl_add_u64 v[224:225], s[26:27], 0, v[156:157]
	global_load_lds_dwordx4 v[186:187], off sc0
	s_mov_b32 m0, s38
	s_nop 0
	global_load_lds_dwordx4 v[222:223], off sc0
	s_mov_b32 m0, s39
	s_nop 0
	global_load_lds_dwordx4 v[224:225], off sc0
	ds_read_b128 v[186:189], v179 offset:16384
	ds_read_b128 v[190:193], v179 offset:17408
	ds_read_b128 v[194:197], v179 offset:18432
	ds_read_b128 v[198:201], v179 offset:19456
	ds_read_b128 v[202:205], v179 offset:20480
	ds_read_b128 v[206:209], v179 offset:21504
	ds_read_b128 v[210:213], v179 offset:22528
	ds_read_b128 v[214:217], v179 offset:23552
	s_waitcnt vmcnt(8)
	s_waitcnt lgkmcnt(0)
	s_barrier
	v_mfma_f32_16x16x32_bf16 v[60:63], v[128:131], v[186:189], v[60:63]
	v_mfma_f32_16x16x32_bf16 v[60:63], v[132:135], v[190:193], v[60:63]
	v_mfma_f32_16x16x32_bf16 v[56:59], v[140:143], v[190:193], v[56:59]
	v_mfma_f32_16x16x32_bf16 v[56:59], v[136:139], v[186:189], v[56:59]
	v_mfma_f32_16x16x32_bf16 v[52:55], v[144:147], v[186:189], v[52:55]
	v_mfma_f32_16x16x32_bf16 v[52:55], v[148:151], v[190:193], v[52:55]
	v_mfma_f32_16x16x32_bf16 v[48:51], v[182:185], v[190:193], v[48:51]
	v_mfma_f32_16x16x32_bf16 v[48:51], v[170:173], v[186:189], v[48:51]
	v_mfma_f32_16x16x32_bf16 v[32:35], v[170:173], v[194:197], v[32:35]
	v_mfma_f32_16x16x32_bf16 v[32:35], v[182:185], v[198:201], v[32:35]
	v_mfma_f32_16x16x32_bf16 v[36:39], v[148:151], v[198:201], v[36:39]
	v_mfma_f32_16x16x32_bf16 v[36:39], v[144:147], v[194:197], v[36:39]
	v_mfma_f32_16x16x32_bf16 v[40:43], v[136:139], v[194:197], v[40:43]
	v_mfma_f32_16x16x32_bf16 v[40:43], v[140:143], v[198:201], v[40:43]
	v_mfma_f32_16x16x32_bf16 v[44:47], v[132:135], v[198:201], v[44:47]
	v_mfma_f32_16x16x32_bf16 v[44:47], v[128:131], v[194:197], v[44:47]
	v_mfma_f32_16x16x32_bf16 v[28:31], v[128:131], v[202:205], v[28:31]
	v_mfma_f32_16x16x32_bf16 v[28:31], v[132:135], v[206:209], v[28:31]
	v_mfma_f32_16x16x32_bf16 v[24:27], v[140:143], v[206:209], v[24:27]
	v_mfma_f32_16x16x32_bf16 v[24:27], v[136:139], v[202:205], v[24:27]
	v_mfma_f32_16x16x32_bf16 v[20:23], v[144:147], v[202:205], v[20:23]
	v_mfma_f32_16x16x32_bf16 v[20:23], v[148:151], v[206:209], v[20:23]
	v_mfma_f32_16x16x32_bf16 v[16:19], v[182:185], v[206:209], v[16:19]
	v_mfma_f32_16x16x32_bf16 v[16:19], v[170:173], v[202:205], v[16:19]
	v_mfma_f32_16x16x32_bf16 v[0:3], v[170:173], v[210:213], v[0:3]
	v_mfma_f32_16x16x32_bf16 v[0:3], v[182:185], v[214:217], v[0:3]
	v_mfma_f32_16x16x32_bf16 v[4:7], v[148:151], v[214:217], v[4:7]
	v_mfma_f32_16x16x32_bf16 v[4:7], v[144:147], v[210:213], v[4:7]
	v_mfma_f32_16x16x32_bf16 v[8:11], v[136:139], v[210:213], v[8:11]
	v_mfma_f32_16x16x32_bf16 v[8:11], v[140:143], v[214:217], v[8:11]
	v_mfma_f32_16x16x32_bf16 v[12:15], v[132:135], v[214:217], v[12:15]
	v_mfma_f32_16x16x32_bf16 v[12:15], v[128:131], v[210:213], v[12:15]
	s_barrier
	s_add_i32 s58, 0, 0x18000
	s_add_i32 s59, 0, 0x1c000
	v_add_u32_e32 v140, s58, v174
	v_add_u32_e32 v181, s59, v174
	ds_read_b128 v[128:131], v140
	ds_read_b128 v[132:135], v140 offset:1024
	ds_read_b128 v[136:139], v140 offset:2048
	ds_read_b128 v[140:143], v140 offset:3072
	ds_read_b128 v[144:147], v181
	ds_read_b128 v[148:151], v181 offset:1024
	ds_read_b128 v[170:173], v181 offset:2048
	ds_read_b128 v[182:185], v181 offset:3072
	s_add_u32 s26, s26, 0x400000
	s_addc_u32 s27, s27, 0
	s_mov_b32 m0, s40
	v_lshl_add_u64 v[186:187], s[26:27], 0, v[152:153]
	global_load_lds_dwordx4 v[186:187], off sc0
	v_lshl_add_u64 v[186:187], s[26:27], 0, v[156:157]
	s_mov_b32 m0, s41
	s_nop 0
	global_load_lds_dwordx4 v[186:187], off sc0
	ds_read_b128 v[186:189], v179 offset:32768
	ds_read_b128 v[190:193], v179 offset:33792
	ds_read_b128 v[194:197], v179 offset:34816
	ds_read_b128 v[198:201], v179 offset:35840
	ds_read_b128 v[202:205], v179 offset:36864
	ds_read_b128 v[206:209], v179 offset:37888
	ds_read_b128 v[210:213], v179 offset:38912
	ds_read_b128 v[214:217], v179 offset:39936
	s_waitcnt vmcnt(8)
	s_waitcnt lgkmcnt(0)
	s_barrier
	v_mfma_f32_16x16x32_bf16 v[124:127], v[128:131], v[186:189], v[124:127]
	v_mfma_f32_16x16x32_bf16 v[124:127], v[132:135], v[190:193], v[124:127]
	v_mfma_f32_16x16x32_bf16 v[120:123], v[140:143], v[190:193], v[120:123]
	v_mfma_f32_16x16x32_bf16 v[120:123], v[136:139], v[186:189], v[120:123]
	v_mfma_f32_16x16x32_bf16 v[116:119], v[144:147], v[186:189], v[116:119]
	v_mfma_f32_16x16x32_bf16 v[116:119], v[148:151], v[190:193], v[116:119]
	v_mfma_f32_16x16x32_bf16 v[112:115], v[182:185], v[190:193], v[112:115]
	v_mfma_f32_16x16x32_bf16 v[112:115], v[170:173], v[186:189], v[112:115]
	v_mfma_f32_16x16x32_bf16 v[96:99], v[170:173], v[194:197], v[96:99]
	v_mfma_f32_16x16x32_bf16 v[96:99], v[182:185], v[198:201], v[96:99]
	v_mfma_f32_16x16x32_bf16 v[100:103], v[148:151], v[198:201], v[100:103]
	v_mfma_f32_16x16x32_bf16 v[100:103], v[144:147], v[194:197], v[100:103]
	v_mfma_f32_16x16x32_bf16 v[104:107], v[136:139], v[194:197], v[104:107]
	v_mfma_f32_16x16x32_bf16 v[104:107], v[140:143], v[198:201], v[104:107]
	v_mfma_f32_16x16x32_bf16 v[108:111], v[132:135], v[198:201], v[108:111]
	v_mfma_f32_16x16x32_bf16 v[108:111], v[128:131], v[194:197], v[108:111]
	v_mfma_f32_16x16x32_bf16 v[92:95], v[128:131], v[202:205], v[92:95]
	v_mfma_f32_16x16x32_bf16 v[92:95], v[132:135], v[206:209], v[92:95]
	v_mfma_f32_16x16x32_bf16 v[88:91], v[140:143], v[206:209], v[88:91]
	v_mfma_f32_16x16x32_bf16 v[88:91], v[136:139], v[202:205], v[88:91]
	v_mfma_f32_16x16x32_bf16 v[84:87], v[144:147], v[202:205], v[84:87]
	v_mfma_f32_16x16x32_bf16 v[84:87], v[148:151], v[206:209], v[84:87]
	v_mfma_f32_16x16x32_bf16 v[80:83], v[182:185], v[206:209], v[80:83]
	v_mfma_f32_16x16x32_bf16 v[80:83], v[170:173], v[202:205], v[80:83]
	v_mfma_f32_16x16x32_bf16 v[64:67], v[170:173], v[210:213], v[64:67]
	v_mfma_f32_16x16x32_bf16 v[64:67], v[182:185], v[214:217], v[64:67]
	v_mfma_f32_16x16x32_bf16 v[68:71], v[148:151], v[214:217], v[68:71]
	v_mfma_f32_16x16x32_bf16 v[68:71], v[144:147], v[210:213], v[68:71]
	v_mfma_f32_16x16x32_bf16 v[72:75], v[136:139], v[210:213], v[72:75]
	v_mfma_f32_16x16x32_bf16 v[72:75], v[140:143], v[214:217], v[72:75]
	v_mfma_f32_16x16x32_bf16 v[76:79], v[132:135], v[214:217], v[76:79]
	v_mfma_f32_16x16x32_bf16 v[76:79], v[128:131], v[210:213], v[76:79]
	s_barrier
	s_add_i32 s26, s58, s37
	v_lshl_add_u64 v[186:187], v[218:219], 0, s[14:15]
	s_mov_b32 m0, s26
	s_nop 0
	global_load_lds_dwordx4 v[186:187], off sc0
	s_add_i32 m0, s26, 0x2000
	s_add_u32 s24, s24, 0x400800
	v_lshl_add_u64 v[186:187], v[220:221], 0, s[14:15]
	s_addc_u32 s25, s25, 0
	s_add_i32 s26, s59, s37
	global_load_lds_dwordx4 v[186:187], off sc0
	v_lshl_add_u64 v[186:187], s[24:25], 0, v[154:155]
	s_mov_b32 m0, s26
	s_nop 0
	global_load_lds_dwordx4 v[186:187], off sc0
	v_lshl_add_u64 v[186:187], s[24:25], 0, v[158:159]
	s_add_i32 m0, s26, 0x2000
	s_nop 0
	global_load_lds_dwordx4 v[186:187], off sc0
	v_lshl_add_u64 v[186:187], v[222:223], 0, s[14:15]
	s_mov_b32 m0, s43
	s_nop 0
	global_load_lds_dwordx4 v[186:187], off sc0
	v_lshl_add_u64 v[186:187], v[224:225], 0, s[14:15]
	s_mov_b32 m0, s44
	s_nop 0
	global_load_lds_dwordx4 v[186:187], off sc0
	ds_read_b128 v[186:189], v179 offset:49152
	ds_read_b128 v[190:193], v179 offset:50176
	ds_read_b128 v[194:197], v179 offset:51200
	ds_read_b128 v[198:201], v179 offset:52224
	ds_read_b128 v[202:205], v179 offset:53248
	ds_read_b128 v[206:209], v179 offset:54272
	ds_read_b128 v[210:213], v179 offset:55296
	ds_read_b128 v[214:217], v179 offset:56320
	s_waitcnt vmcnt(8)
	s_waitcnt lgkmcnt(0)
	s_barrier
	v_mfma_f32_16x16x32_bf16 v[60:63], v[128:131], v[186:189], v[60:63]
	v_mfma_f32_16x16x32_bf16 v[60:63], v[132:135], v[190:193], v[60:63]
	v_mfma_f32_16x16x32_bf16 v[56:59], v[140:143], v[190:193], v[56:59]
	v_mfma_f32_16x16x32_bf16 v[56:59], v[136:139], v[186:189], v[56:59]
	v_mfma_f32_16x16x32_bf16 v[52:55], v[144:147], v[186:189], v[52:55]
	v_mfma_f32_16x16x32_bf16 v[52:55], v[148:151], v[190:193], v[52:55]
	v_mfma_f32_16x16x32_bf16 v[48:51], v[182:185], v[190:193], v[48:51]
	v_mfma_f32_16x16x32_bf16 v[48:51], v[170:173], v[186:189], v[48:51]
	v_mfma_f32_16x16x32_bf16 v[32:35], v[170:173], v[194:197], v[32:35]
	v_mfma_f32_16x16x32_bf16 v[32:35], v[182:185], v[198:201], v[32:35]
	v_mfma_f32_16x16x32_bf16 v[36:39], v[148:151], v[198:201], v[36:39]
	v_mfma_f32_16x16x32_bf16 v[36:39], v[144:147], v[194:197], v[36:39]
	v_mfma_f32_16x16x32_bf16 v[40:43], v[136:139], v[194:197], v[40:43]
	v_mfma_f32_16x16x32_bf16 v[40:43], v[140:143], v[198:201], v[40:43]
	v_mfma_f32_16x16x32_bf16 v[44:47], v[132:135], v[198:201], v[44:47]
	v_mfma_f32_16x16x32_bf16 v[44:47], v[128:131], v[194:197], v[44:47]
	v_mfma_f32_16x16x32_bf16 v[28:31], v[128:131], v[202:205], v[28:31]
	v_mfma_f32_16x16x32_bf16 v[28:31], v[132:135], v[206:209], v[28:31]
	v_mfma_f32_16x16x32_bf16 v[24:27], v[140:143], v[206:209], v[24:27]
	v_mfma_f32_16x16x32_bf16 v[24:27], v[136:139], v[202:205], v[24:27]
	v_mfma_f32_16x16x32_bf16 v[20:23], v[144:147], v[202:205], v[20:23]
	v_mfma_f32_16x16x32_bf16 v[20:23], v[148:151], v[206:209], v[20:23]
	v_mfma_f32_16x16x32_bf16 v[16:19], v[182:185], v[206:209], v[16:19]
	v_mfma_f32_16x16x32_bf16 v[16:19], v[170:173], v[202:205], v[16:19]
	v_mfma_f32_16x16x32_bf16 v[0:3], v[170:173], v[210:213], v[0:3]
	v_mfma_f32_16x16x32_bf16 v[0:3], v[182:185], v[214:217], v[0:3]
	v_mfma_f32_16x16x32_bf16 v[4:7], v[148:151], v[214:217], v[4:7]
	v_mfma_f32_16x16x32_bf16 v[4:7], v[144:147], v[210:213], v[4:7]
	v_mfma_f32_16x16x32_bf16 v[8:11], v[136:139], v[210:213], v[8:11]
	v_mfma_f32_16x16x32_bf16 v[8:11], v[140:143], v[214:217], v[8:11]
	v_mfma_f32_16x16x32_bf16 v[12:15], v[132:135], v[214:217], v[12:15]
	v_mfma_f32_16x16x32_bf16 v[12:15], v[128:131], v[210:213], v[12:15]
	s_barrier
	s_add_i32 s57, s57, 2
	s_add_u32 s22, s22, 0x1000
	s_addc_u32 s23, s23, 0
	s_add_u32 s55, s55, 0x1000
	s_addc_u32 s56, s56, 0
	s_cmpk_gt_u32 s57, 0xfd
	s_cbranch_scc0 .LBB0_1625
